# opt16c: row-scale loads first in the queue, GEMM setup + 14 DMA pieces behind them, reduction after the pieces (barrier kept, its wait dropped); on v068
# baseline (speedup 1.0000x reference)
.LBB0_194:
	s_waitcnt lgkmcnt(0)
	s_add_u32 s18, s70, 0x1b700000
	s_addc_u32 s19, s71, 0
	s_add_u32 s14, s70, 0x7700000
	s_addc_u32 s15, s71, 0
	s_add_u32 s16, s70, 0xf700000
	s_addc_u32 s17, s71, 0
	s_cmp_lt_i32 s74, 3
	s_cselect_b64 s[0:1], -1, 0
	s_cmp_gt_i32 s75, 2
	s_cselect_b64 s[4:5], -1, 0
	s_and_b64 s[0:1], s[0:1], s[4:5]
	s_andn2_b64 vcc, exec, s[0:1]
	v_lshrrev_b32_e32 v129, 8, v128
	s_cbranch_vccnz .LBB0_303
	v_lshlrev_b32_e32 v8, 2, v128
	s_ashr_i32 s3, s2, 31
	v_add_u32_e32 v0, 0, v8
	s_ashr_i32 s56, s72, 31
	s_mov_b32 s57, s72
	v_and_b32_e32 v4, 0xff, v128
	v_add_u32_e32 v5, 0xfffffe00, v128
	v_add_u32_e32 v6, 0x20000, v0
	v_lshrrev_b32_e32 v7, 8, v128
	s_mov_b64 s[0:1], 0
	v_mov_b64_e32 v[0:1], s[2:3]
	s_mov_b64 s[4:5], 0x600
	s_mov_b32 s10, 0x2aaaaaab
	s_movk_i32 s11, 0x60
	v_mov_b32_e32 v9, 0x358637bd
	s_movk_i32 s12, 0x8ff
	v_mov_b32_e32 v10, 0xc0
	v_mov_b32_e32 v11, 0xc1
	v_and_b32_e32 v114, 0xff, v128
	s_lshr_b32 s98, s91, 2
	v_mov_b32_e32 v115, 0x358637bd
	s_mul_i32 s99, s98, s72
	s_add_i32 s99, s99, s2
	s_cmp_lt_u32 s99, 0x600
	s_cselect_b32 s99, s99, s2
	s_and_b32 s100, s99, 7
	s_mul_i32 s100, s100, 0xc0
	s_lshr_b32 s101, s99, 3
	s_add_i32 s100, s100, s101
	s_mul_hi_u32 s101, s100, 0x2aaaaab
	s_lshl_b32 s101, s101, 3
	s_and_b32 s100, s100, 7
	s_or_b32 s101, s101, s100
	s_lshl_b32 s101, s101, 8
	v_add_u32_e32 v112, s101, v114
	v_lshlrev_b32_e32 v112, 6, v112
	v_mov_b32_e32 v113, 0
	v_lshl_add_u64 v[112:113], s[18:19], 0, v[112:113]
	global_load_dwordx4 v[16:19], v[112:113], off
	global_load_dwordx4 v[20:23], v[112:113], off offset:16
	global_load_dwordx4 v[24:27], v[112:113], off offset:32
	global_load_dwordx4 v[28:31], v[112:113], off offset:48
	s_add_i32 s98, s98, 2
	s_mul_i32 s99, s98, s72
	s_add_i32 s99, s99, s2
	s_cmp_lt_u32 s99, 0x600
	s_cselect_b32 s99, s99, s2
	s_and_b32 s100, s99, 7
	s_mul_i32 s100, s100, 0xc0
	s_lshr_b32 s101, s99, 3
	s_add_i32 s100, s100, s101
	s_mul_hi_u32 s101, s100, 0x2aaaaab
	s_lshl_b32 s101, s101, 3
	s_and_b32 s100, s100, 7
	s_or_b32 s101, s101, s100
	s_lshl_b32 s101, s101, 8
	v_add_u32_e32 v112, s101, v114
	v_lshlrev_b32_e32 v112, 6, v112
	v_mov_b32_e32 v113, 0
	v_lshl_add_u64 v[112:113], s[18:19], 0, v[112:113]
	global_load_dwordx4 v[32:35], v[112:113], off
	global_load_dwordx4 v[36:39], v[112:113], off offset:16
	global_load_dwordx4 v[40:43], v[112:113], off offset:32
	global_load_dwordx4 v[44:47], v[112:113], off offset:48
	s_add_i32 s98, s98, 2
	s_mul_i32 s99, s98, s72
	s_add_i32 s99, s99, s2
	s_cmp_lt_u32 s99, 0x600
	s_cselect_b32 s99, s99, s2
	s_and_b32 s100, s99, 7
	s_mul_i32 s100, s100, 0xc0
	s_lshr_b32 s101, s99, 3
	s_add_i32 s100, s100, s101
	s_mul_hi_u32 s101, s100, 0x2aaaaab
	s_lshl_b32 s101, s101, 3
	s_and_b32 s100, s100, 7
	s_or_b32 s101, s101, s100
	s_lshl_b32 s101, s101, 8
	v_add_u32_e32 v112, s101, v114
	v_lshlrev_b32_e32 v112, 6, v112
	v_mov_b32_e32 v113, 0
	v_lshl_add_u64 v[112:113], s[18:19], 0, v[112:113]
	global_load_dwordx4 v[48:51], v[112:113], off
	global_load_dwordx4 v[52:55], v[112:113], off offset:16
	global_load_dwordx4 v[56:59], v[112:113], off offset:32
	global_load_dwordx4 v[60:63], v[112:113], off offset:48
	s_add_i32 s98, s98, 2
.LBB0_199:
	s_or_b64 exec, exec, s[0:1]
	s_cmpk_lt_i32 s2, 0x600
	s_cselect_b64 s[4:5], -1, 0
	s_cmpk_gt_i32 s2, 0x5ff
	v_readfirstlane_b32 s8, v128
	s_barrier
	s_cbranch_scc0 .LBB0_202
	s_andn2_b64 vcc, exec, s[4:5]
	s_cbranch_vccz .LBB0_203

.LBB0_203:
	v_lshrrev_b32_e32 v2, 1, v128
	v_and_b32_e32 v132, 24, v2
	v_lshrrev_b32_e32 v2, 5, v128
	v_and_b32_e32 v2, 4, v2
	v_bfe_u32 v3, v128, 2, 2
	v_lshlrev_b32_e32 v0, 4, v128
	v_and_b32_e32 v1, 32, v128
	v_bfe_u32 v11, v128, 2, 4
	v_or3_b32 v2, v2, v3, v132
	v_lshrrev_b32_e32 v3, 3, v128
	s_movk_i32 s1, 0x70
	v_bitop3_b32 v9, v0, v1, 48 bitop3:0x6c
	v_and_b32_e32 v10, 64, v128
	v_and_or_b32 v4, v3, s1, v11
	s_movk_i32 s1, 0x60
	v_add_u32_e32 v12, 0x2000, v0
	s_lshr_b32 s5, s8, 6
	s_lshr_b32 s4, s8, 8
	v_or_b32_e32 v1, v9, v10
	v_and_or_b32 v3, v3, s1, v2
	v_lshrrev_b32_e32 v0, 7, v12
	s_movk_i32 s1, 0xf0
	s_lshl_b32 s58, s5, 10
	v_lshl_or_b32 v136, v3, 11, v1
	v_and_or_b32 v3, v0, s1, v11
	s_movk_i32 s1, 0xe0
	s_add_u32 s59, s70, 0x100000
	v_and_or_b32 v0, v0, s1, v2
	s_addc_u32 s62, s71, 0
	s_ashr_i32 s7, s6, 31
	s_ashr_i32 s1, s0, 31
	s_lshl_b64 s[10:11], s[6:7], 19
	s_lshl_b64 s[12:13], s[0:1], 19
	s_add_u32 s52, s59, s12
	s_addc_u32 s53, s62, s13
	s_add_i32 s63, s58, 0
	s_add_i32 m0, s63, 0x10000
	v_lshl_or_b32 v140, v0, 11, v1
	global_load_lds_dwordx4 v136, s[52:53]
	s_add_i32 m0, s63, 0x12000
	s_add_u32 s12, s52, 0x40000
	global_load_lds_dwordx4 v140, s[52:53]
	s_addc_u32 s13, s53, 0
	s_add_i32 m0, s63, 0x14000
	v_lshl_or_b32 v134, v4, 11, v1
	global_load_lds_dwordx4 v136, s[12:13]
	s_add_i32 m0, s63, 0x16000
	s_add_u32 s50, s14, s10
	s_addc_u32 s51, s15, s11
	s_add_i32 s64, s63, 0x2000
	global_load_lds_dwordx4 v140, s[12:13]
	s_mov_b32 m0, s63
	s_add_u32 s10, s50, 0x40000
	v_lshl_or_b32 v138, v3, 11, v1
	global_load_lds_dwordx4 v134, s[50:51]
	s_mov_b32 m0, s64
	s_addc_u32 s11, s51, 0
	s_add_i32 s65, s63, 0x4000
	global_load_lds_dwordx4 v138, s[50:51]
	s_mov_b32 m0, s65
	s_add_i32 s66, s63, 0x6000
	global_load_lds_dwordx4 v134, s[10:11]
	s_mov_b32 m0, s66
	v_mov_b32_e32 v143, 0
	global_load_lds_dwordx4 v138, s[10:11]
	v_mov_b32_e32 v137, v143
	v_mov_b32_e32 v141, v143
	v_mov_b32_e32 v135, v143
	v_mov_b32_e32 v139, v143
	s_cmp_eq_u32 s4, 1
	s_mov_b32 s9, 0
	v_lshl_add_u64 v[6:7], s[52:53], 0, v[136:137]
	v_lshl_add_u64 v[4:5], s[52:53], 0, v[140:141]
	v_lshl_add_u64 v[0:1], s[50:51], 0, v[134:135]
	s_cselect_b64 s[10:11], -1, 0
	v_lshl_add_u64 v[2:3], s[50:51], 0, v[138:139]
	s_add_u32 s20, s70, 0x13700000
	s_addc_u32 s21, s71, 0
	s_lshl_b32 s5, s5, 5
	s_mov_b64 s[22:23], 0x80
	s_and_b32 s67, s5, 0x60
	s_add_i32 m0, s63, 0x18000
	v_lshl_add_u64 v[6:7], v[6:7], 0, s[22:23]
	s_lshl_b32 s1, s4, 13
	s_lshl_b32 s5, s67, 7
	global_load_lds_dwordx4 v[6:7], off
	v_lshl_add_u64 v[4:5], v[4:5], 0, s[22:23]
	s_add_i32 m0, s63, 0x1a000
	s_add_i32 s79, s63, 0x8000
	s_add_i32 s81, s63, 0xa000
	global_load_lds_dwordx4 v[4:5], off
	v_lshl_add_u64 v[0:1], v[0:1], 0, s[22:23]
	s_mov_b32 m0, s79
	s_add_u32 s12, s52, 0x40080
	global_load_lds_dwordx4 v[0:1], off
	v_lshl_add_u64 v[0:1], v[2:3], 0, s[22:23]
	s_mov_b32 m0, s81
	s_addc_u32 s13, s53, 0
	global_load_lds_dwordx4 v[0:1], off
	s_add_i32 m0, s63, 0x1c000
	v_lshl_add_u64 v[0:1], s[12:13], 0, v[136:137]
	global_load_lds_dwordx4 v[0:1], off
	v_lshl_add_u64 v[0:1], s[12:13], 0, v[140:141]
	s_add_i32 m0, s63, 0x1e000
	global_load_lds_dwordx4 v[0:1], off
	v_lshlrev_b32_e32 v116, 2, v128
	v_add_u32_e32 v116, 0x20000, v116
	s_waitcnt vmcnt(22)
	v_pk_add_f32 v[118:119], v[18:19], v[22:23]
	v_pk_add_f32 v[120:121], v[16:17], v[20:21]
	v_pk_add_f32 v[122:123], v[26:27], v[30:31]
	v_pk_add_f32 v[124:125], v[24:25], v[28:29]
	v_pk_add_f32 v[118:119], v[118:119], v[122:123]
	v_pk_add_f32 v[120:121], v[120:121], v[124:125]
	v_add_f32_e32 v120, v121, v120
	v_add_f32_e32 v118, v118, v119
	v_add_f32_e32 v118, v120, v118
	v_fmamk_f32 v118, v118, 0x3a800000, v115
	v_rsq_f32_e32 v118, v118
	ds_write_b32 v116, v118
	s_waitcnt vmcnt(18)
	v_pk_add_f32 v[118:119], v[34:35], v[38:39]
	v_pk_add_f32 v[120:121], v[32:33], v[36:37]
	v_pk_add_f32 v[122:123], v[42:43], v[46:47]
	v_pk_add_f32 v[124:125], v[40:41], v[44:45]
	v_pk_add_f32 v[118:119], v[118:119], v[122:123]
	v_pk_add_f32 v[120:121], v[120:121], v[124:125]
	v_add_f32_e32 v120, v121, v120
	v_add_f32_e32 v118, v118, v119
	v_add_f32_e32 v118, v120, v118
	v_fmamk_f32 v118, v118, 0x3a800000, v115
	v_rsq_f32_e32 v118, v118
	ds_write_b32 v116, v118 offset:2048
	s_waitcnt vmcnt(14)
	v_pk_add_f32 v[118:119], v[50:51], v[54:55]
	v_pk_add_f32 v[120:121], v[48:49], v[52:53]
	v_pk_add_f32 v[122:123], v[58:59], v[62:63]
	v_pk_add_f32 v[124:125], v[56:57], v[60:61]
	v_pk_add_f32 v[118:119], v[118:119], v[122:123]
	v_pk_add_f32 v[120:121], v[120:121], v[124:125]
	v_add_f32_e32 v120, v121, v120
	v_add_f32_e32 v118, v118, v119
	v_add_f32_e32 v118, v120, v118
	v_fmamk_f32 v118, v118, 0x3a800000, v115
	v_rsq_f32_e32 v118, v118
	ds_write_b32 v116, v118 offset:4096
	s_cmp_lg_u32 s4, 1
	s_cbranch_scc1 .LBB0_205
	s_barrier

.LBB0_462:
	s_cmp_lt_i32 s74, 6
	s_cselect_b64 s[0:1], -1, 0
	s_cmp_gt_i32 s75, 5
	s_cselect_b64 s[4:5], -1, 0
	s_and_b64 s[0:1], s[0:1], s[4:5]
	s_andn2_b64 vcc, exec, s[0:1]
	s_cbranch_vccnz .LBB0_537
	v_lshlrev_b32_e32 v8, 2, v128
	s_ashr_i32 s3, s2, 31
	v_add_u32_e32 v0, 0, v8
	s_ashr_i32 s52, s72, 31
	s_mov_b32 s53, s72
	v_and_b32_e32 v4, 0xff, v128
	v_add_u32_e32 v5, 0xfffffe00, v128
	v_add_u32_e32 v6, 0x20000, v0
	v_lshrrev_b32_e32 v7, 8, v128
	s_mov_b64 s[0:1], 0
	s_waitcnt lgkmcnt(0)
	v_mov_b64_e32 v[0:1], s[2:3]
	s_mov_b64 s[4:5], 0xb00
	s_mov_b32 s10, 0x2e8ba2e9
	s_movk_i32 s11, 0xb0
	v_mov_b32_e32 v9, 0x358637bd
	s_movk_i32 s12, 0x8ff
	v_mov_b32_e32 v10, 0x160
	v_mov_b32_e32 v11, 0x161
	v_and_b32_e32 v114, 0xff, v128
	s_lshr_b32 s98, s91, 2
	v_mov_b32_e32 v115, 0x358637bd
	s_mul_i32 s99, s98, s72
	s_add_i32 s99, s99, s2
	s_cmp_lt_u32 s99, 0xb00
	s_cselect_b32 s99, s99, s2
	s_and_b32 s100, s99, 7
	s_mul_i32 s100, s100, 0x160
	s_lshr_b32 s101, s99, 3
	s_add_i32 s100, s100, s101
	s_mul_hi_u32 s101, s100, 0x1745d18
	s_lshl_b32 s101, s101, 3
	s_and_b32 s100, s100, 7
	s_or_b32 s101, s101, s100
	s_lshl_b32 s101, s101, 8
	v_add_u32_e32 v112, s101, v114
	v_lshlrev_b32_e32 v112, 6, v112
	v_mov_b32_e32 v113, 0
	v_lshl_add_u64 v[112:113], s[18:19], 0, v[112:113]
	global_load_dwordx4 v[16:19], v[112:113], off
	global_load_dwordx4 v[20:23], v[112:113], off offset:16
	global_load_dwordx4 v[24:27], v[112:113], off offset:32
	global_load_dwordx4 v[28:31], v[112:113], off offset:48
	s_add_i32 s98, s98, 2
	s_mul_i32 s99, s98, s72
	s_add_i32 s99, s99, s2
	s_cmp_lt_u32 s99, 0xb00
	s_cselect_b32 s99, s99, s2
	s_and_b32 s100, s99, 7
	s_mul_i32 s100, s100, 0x160
	s_lshr_b32 s101, s99, 3
	s_add_i32 s100, s100, s101
	s_mul_hi_u32 s101, s100, 0x1745d18
	s_lshl_b32 s101, s101, 3
	s_and_b32 s100, s100, 7
	s_or_b32 s101, s101, s100
	s_lshl_b32 s101, s101, 8
	v_add_u32_e32 v112, s101, v114
	v_lshlrev_b32_e32 v112, 6, v112
	v_mov_b32_e32 v113, 0
	v_lshl_add_u64 v[112:113], s[18:19], 0, v[112:113]
	global_load_dwordx4 v[32:35], v[112:113], off
	global_load_dwordx4 v[36:39], v[112:113], off offset:16
	global_load_dwordx4 v[40:43], v[112:113], off offset:32
	global_load_dwordx4 v[44:47], v[112:113], off offset:48
	s_add_i32 s98, s98, 2
	s_mul_i32 s99, s98, s72
	s_add_i32 s99, s99, s2
	s_cmp_lt_u32 s99, 0xb00
	s_cselect_b32 s99, s99, s2
	s_and_b32 s100, s99, 7
	s_mul_i32 s100, s100, 0x160
	s_lshr_b32 s101, s99, 3
	s_add_i32 s100, s100, s101
	s_mul_hi_u32 s101, s100, 0x1745d18
	s_lshl_b32 s101, s101, 3
	s_and_b32 s100, s100, 7
	s_or_b32 s101, s101, s100
	s_lshl_b32 s101, s101, 8
	v_add_u32_e32 v112, s101, v114
	v_lshlrev_b32_e32 v112, 6, v112
	v_mov_b32_e32 v113, 0
	v_lshl_add_u64 v[112:113], s[18:19], 0, v[112:113]
	global_load_dwordx4 v[48:51], v[112:113], off
	global_load_dwordx4 v[52:55], v[112:113], off offset:16
	global_load_dwordx4 v[56:59], v[112:113], off offset:32
	global_load_dwordx4 v[60:63], v[112:113], off offset:48
	s_add_i32 s98, s98, 2
	s_mul_i32 s99, s98, s72
	s_add_i32 s99, s99, s2
	s_cmp_lt_u32 s99, 0xb00
	s_cselect_b32 s99, s99, s2
	s_and_b32 s100, s99, 7
	s_mul_i32 s100, s100, 0x160
	s_lshr_b32 s101, s99, 3
	s_add_i32 s100, s100, s101
	s_mul_hi_u32 s101, s100, 0x1745d18
	s_lshl_b32 s101, s101, 3
	s_and_b32 s100, s100, 7
	s_or_b32 s101, s101, s100
	s_lshl_b32 s101, s101, 8
	v_add_u32_e32 v112, s101, v114
	v_lshlrev_b32_e32 v112, 6, v112
	v_mov_b32_e32 v113, 0
	v_lshl_add_u64 v[112:113], s[18:19], 0, v[112:113]
	global_load_dwordx4 v[64:67], v[112:113], off
	global_load_dwordx4 v[68:71], v[112:113], off offset:16
	global_load_dwordx4 v[72:75], v[112:113], off offset:32
	global_load_dwordx4 v[76:79], v[112:113], off offset:48
	s_add_i32 s98, s98, 2
	s_mul_i32 s99, s98, s72
	s_add_i32 s99, s99, s2
	s_cmp_lt_u32 s99, 0xb00
	s_cselect_b32 s99, s99, s2
	s_and_b32 s100, s99, 7
	s_mul_i32 s100, s100, 0x160
	s_lshr_b32 s101, s99, 3
	s_add_i32 s100, s100, s101
	s_mul_hi_u32 s101, s100, 0x1745d18
	s_lshl_b32 s101, s101, 3
	s_and_b32 s100, s100, 7
	s_or_b32 s101, s101, s100
	s_lshl_b32 s101, s101, 8
	v_add_u32_e32 v112, s101, v114
	v_lshlrev_b32_e32 v112, 6, v112
	v_mov_b32_e32 v113, 0
	v_lshl_add_u64 v[112:113], s[18:19], 0, v[112:113]
	global_load_dwordx4 v[80:83], v[112:113], off
	global_load_dwordx4 v[84:87], v[112:113], off offset:16
	global_load_dwordx4 v[88:91], v[112:113], off offset:32
	global_load_dwordx4 v[92:95], v[112:113], off offset:48
	s_add_i32 s98, s98, 2
	s_mul_i32 s99, s98, s72
	s_add_i32 s99, s99, s2
	s_cmp_lt_u32 s99, 0xb00
	s_cselect_b32 s99, s99, s2
	s_and_b32 s100, s99, 7
	s_mul_i32 s100, s100, 0x160
	s_lshr_b32 s101, s99, 3
	s_add_i32 s100, s100, s101
	s_mul_hi_u32 s101, s100, 0x1745d18
	s_lshl_b32 s101, s101, 3
	s_and_b32 s100, s100, 7
	s_or_b32 s101, s101, s100
	s_lshl_b32 s101, s101, 8
	v_add_u32_e32 v112, s101, v114
	v_lshlrev_b32_e32 v112, 6, v112
	v_mov_b32_e32 v113, 0
	v_lshl_add_u64 v[112:113], s[18:19], 0, v[112:113]
	global_load_dwordx4 v[96:99], v[112:113], off
	global_load_dwordx4 v[100:103], v[112:113], off offset:16
	global_load_dwordx4 v[104:107], v[112:113], off offset:32
	global_load_dwordx4 v[108:111], v[112:113], off offset:48
	s_add_i32 s98, s98, 2
.LBB0_467:
	s_or_b64 exec, exec, s[0:1]
	s_cmpk_gt_i32 s2, 0xaff
	v_readfirstlane_b32 s5, v128
	s_barrier
	s_cbranch_scc1 .LBB0_483
	v_lshrrev_b32_e32 v0, 5, v128
	v_lshrrev_b32_e32 v2, 1, v128
	v_and_b32_e32 v0, 4, v0
	v_bfe_u32 v1, v128, 2, 2
	v_and_b32_e32 v12, 24, v2
	v_or3_b32 v0, v0, v1, v12
	v_lshlrev_b32_e32 v1, 4, v128
	v_add_u32_e32 v9, 0x2000, v1
	v_lshrrev_b32_e32 v2, 7, v9
	s_movk_i32 s0, 0xe0
	v_and_b32_e32 v4, 32, v128
	v_and_or_b32 v3, v2, s0, v0
	v_bitop3_b32 v10, v1, v4, 48 bitop3:0x6c
	v_and_b32_e32 v11, 64, v128
	v_bfe_u32 v13, v128, 2, 4
	s_movk_i32 s0, 0xf0
	s_lshr_b32 s6, s5, 6
	v_or_b32_e32 v1, v10, v11
	v_and_or_b32 v2, v2, s0, v13
	s_lshr_b32 s10, s5, 8
	s_lshl_b32 s54, s6, 10
	v_lshl_or_b32 v134, v2, 11, v1
	v_lshrrev_b32_e32 v2, 3, v128
	s_movk_i32 s0, 0x60
	s_add_u32 s55, s70, 0x900000
	v_and_or_b32 v0, v2, s0, v0
	s_movk_i32 s0, 0x70
	s_addc_u32 s56, s71, 0
	v_lshl_or_b32 v136, v0, 11, v1
	v_and_or_b32 v0, v2, s0, v13
	s_lshr_b32 s0, s3, 29
	s_add_i32 s0, s2, s0
	s_ashr_i32 s1, s0, 3
	s_and_b32 s0, s0, -8
	s_sub_i32 s0, s2, s0
	s_cmp_lt_i32 s0, 0
	s_movk_i32 s57, 0x161
	s_cselect_b32 s4, s57, 0x160
	s_mul_i32 s0, s0, s4
	s_add_i32 s0, s0, s1
	s_mul_hi_i32 s1, s0, 0x2e8ba2e9
	s_lshr_b32 s4, s1, 31
	s_ashr_i32 s1, s1, 5
	s_add_i32 s1, s1, s4
	s_lshl_b32 s7, s1, 3
	s_mulk_i32 s1, 0xb0
	s_sub_i32 s0, s0, s1
	s_bfe_u32 s1, s0, 0x3001c
	s_add_i32 s1, s0, s1
	s_sext_i32_i16 s4, s1
	s_and_b32 s1, s1, 0xfff8
	s_sub_i32 s0, s0, s1
	s_sext_i32_i16 s0, s0
	s_lshr_b32 s4, s4, 3
	s_add_i32 s40, s7, s0
	s_ashr_i32 s41, s40, 31
	s_bfe_i64 s[8:9], s[4:5], 0x100000
	s_lshl_b64 s[0:1], s[40:41], 19
	s_lshl_b64 s[8:9], s[8:9], 19
	s_add_u32 s48, s55, s8
	s_addc_u32 s49, s56, s9
	s_add_i32 s41, s54, 0
	s_add_i32 m0, s41, 0x10000
	v_lshl_or_b32 v132, v3, 11, v1
	global_load_lds_dwordx4 v136, s[48:49]
	s_add_i32 m0, s41, 0x12000
	s_add_u32 s8, s48, 0x40000
	global_load_lds_dwordx4 v132, s[48:49]
	s_addc_u32 s9, s49, 0
	s_add_i32 m0, s41, 0x14000
	v_lshl_or_b32 v138, v0, 11, v1
	global_load_lds_dwordx4 v136, s[8:9]
	s_add_i32 m0, s41, 0x16000
	s_add_u32 s42, s14, s0
	s_addc_u32 s43, s15, s1
	s_add_i32 s58, s41, 0x2000
	global_load_lds_dwordx4 v132, s[8:9]
	s_mov_b32 m0, s41
	s_add_u32 s0, s42, 0x40000
	global_load_lds_dwordx4 v138, s[42:43]
	s_mov_b32 m0, s58
	s_addc_u32 s1, s43, 0
	s_add_i32 s59, s41, 0x4000
	global_load_lds_dwordx4 v134, s[42:43]
	s_mov_b32 m0, s59
	s_add_i32 s62, s41, 0x6000
	global_load_lds_dwordx4 v138, s[0:1]
	s_mov_b32 m0, s62
	v_mov_b32_e32 v137, 0
	global_load_lds_dwordx4 v134, s[0:1]
	v_mov_b32_e32 v133, v137
	v_mov_b32_e32 v139, v137
	v_mov_b32_e32 v135, v137
	s_cmp_eq_u32 s10, 1
	s_mov_b32 s12, 0
	v_lshl_add_u64 v[6:7], s[48:49], 0, v[136:137]
	v_lshl_add_u64 v[4:5], s[48:49], 0, v[132:133]
	v_lshl_add_u64 v[0:1], s[42:43], 0, v[138:139]
	s_cselect_b64 s[0:1], -1, 0
	v_lshl_add_u64 v[2:3], s[42:43], 0, v[134:135]
	s_lshl_b32 s6, s6, 5
	s_and_b32 s22, s6, 0x60
	s_mov_b64 s[6:7], 0x80
	s_add_i32 m0, s41, 0x18000
	v_lshl_add_u64 v[6:7], v[6:7], 0, s[6:7]
	s_lshl_b32 s11, s10, 13
	s_lshl_b32 s23, s22, 7
	global_load_lds_dwordx4 v[6:7], off
	v_lshl_add_u64 v[4:5], v[4:5], 0, s[6:7]
	s_add_i32 m0, s41, 0x1a000
	s_add_i32 s63, s41, 0x8000
	s_add_i32 s64, s41, 0xa000
	global_load_lds_dwordx4 v[4:5], off
	v_lshl_add_u64 v[0:1], v[0:1], 0, s[6:7]
	s_mov_b32 m0, s63
	s_add_u32 s8, s48, 0x40080
	global_load_lds_dwordx4 v[0:1], off
	v_lshl_add_u64 v[0:1], v[2:3], 0, s[6:7]
	s_mov_b32 m0, s64
	s_addc_u32 s9, s49, 0
	global_load_lds_dwordx4 v[0:1], off
	s_add_i32 m0, s41, 0x1c000
	v_lshl_add_u64 v[0:1], s[8:9], 0, v[136:137]
	global_load_lds_dwordx4 v[0:1], off
	v_lshl_add_u64 v[0:1], s[8:9], 0, v[132:133]
	s_add_i32 m0, s41, 0x1e000
	s_sext_i32_i16 s13, s4
	global_load_lds_dwordx4 v[0:1], off
	v_lshlrev_b32_e32 v116, 2, v128
	v_add_u32_e32 v116, 0x20000, v116
	s_waitcnt vmcnt(34)
	v_pk_add_f32 v[118:119], v[18:19], v[22:23]
	v_pk_add_f32 v[120:121], v[16:17], v[20:21]
	v_pk_add_f32 v[122:123], v[26:27], v[30:31]
	v_pk_add_f32 v[124:125], v[24:25], v[28:29]
	v_pk_add_f32 v[118:119], v[118:119], v[122:123]
	v_pk_add_f32 v[120:121], v[120:121], v[124:125]
	v_add_f32_e32 v120, v121, v120
	v_add_f32_e32 v118, v118, v119
	v_add_f32_e32 v118, v120, v118
	v_fmamk_f32 v118, v118, 0x3a800000, v115
	v_rsq_f32_e32 v118, v118
	ds_write_b32 v116, v118
	s_waitcnt vmcnt(30)
	v_pk_add_f32 v[118:119], v[34:35], v[38:39]
	v_pk_add_f32 v[120:121], v[32:33], v[36:37]
	v_pk_add_f32 v[122:123], v[42:43], v[46:47]
	v_pk_add_f32 v[124:125], v[40:41], v[44:45]
	v_pk_add_f32 v[118:119], v[118:119], v[122:123]
	v_pk_add_f32 v[120:121], v[120:121], v[124:125]
	v_add_f32_e32 v120, v121, v120
	v_add_f32_e32 v118, v118, v119
	v_add_f32_e32 v118, v120, v118
	v_fmamk_f32 v118, v118, 0x3a800000, v115
	v_rsq_f32_e32 v118, v118
	ds_write_b32 v116, v118 offset:2048
	s_waitcnt vmcnt(26)
	v_pk_add_f32 v[118:119], v[50:51], v[54:55]
	v_pk_add_f32 v[120:121], v[48:49], v[52:53]
	v_pk_add_f32 v[122:123], v[58:59], v[62:63]
	v_pk_add_f32 v[124:125], v[56:57], v[60:61]
	v_pk_add_f32 v[118:119], v[118:119], v[122:123]
	v_pk_add_f32 v[120:121], v[120:121], v[124:125]
	v_add_f32_e32 v120, v121, v120
	v_add_f32_e32 v118, v118, v119
	v_add_f32_e32 v118, v120, v118
	v_fmamk_f32 v118, v118, 0x3a800000, v115
	v_rsq_f32_e32 v118, v118
	ds_write_b32 v116, v118 offset:4096
	s_waitcnt vmcnt(22)
	v_pk_add_f32 v[118:119], v[66:67], v[70:71]
	v_pk_add_f32 v[120:121], v[64:65], v[68:69]
	v_pk_add_f32 v[122:123], v[74:75], v[78:79]
	v_pk_add_f32 v[124:125], v[72:73], v[76:77]
	v_pk_add_f32 v[118:119], v[118:119], v[122:123]
	v_pk_add_f32 v[120:121], v[120:121], v[124:125]
	v_add_f32_e32 v120, v121, v120
	v_add_f32_e32 v118, v118, v119
	v_add_f32_e32 v118, v120, v118
	v_fmamk_f32 v118, v118, 0x3a800000, v115
	v_rsq_f32_e32 v118, v118
	ds_write_b32 v116, v118 offset:6144
	s_waitcnt vmcnt(18)
	v_pk_add_f32 v[118:119], v[82:83], v[86:87]
	v_pk_add_f32 v[120:121], v[80:81], v[84:85]
	v_pk_add_f32 v[122:123], v[90:91], v[94:95]
	v_pk_add_f32 v[124:125], v[88:89], v[92:93]
	v_pk_add_f32 v[118:119], v[118:119], v[122:123]
	v_pk_add_f32 v[120:121], v[120:121], v[124:125]
	v_add_f32_e32 v120, v121, v120
	v_add_f32_e32 v118, v118, v119
	v_add_f32_e32 v118, v120, v118
	v_fmamk_f32 v118, v118, 0x3a800000, v115
	v_rsq_f32_e32 v118, v118
	ds_write_b32 v116, v118 offset:8192
	s_waitcnt vmcnt(14)
	v_pk_add_f32 v[118:119], v[98:99], v[102:103]
	v_pk_add_f32 v[120:121], v[96:97], v[100:101]
	v_pk_add_f32 v[122:123], v[106:107], v[110:111]
	v_pk_add_f32 v[124:125], v[104:105], v[108:109]
	v_pk_add_f32 v[118:119], v[118:119], v[122:123]
	v_pk_add_f32 v[120:121], v[120:121], v[124:125]
	v_add_f32_e32 v120, v121, v120
	v_add_f32_e32 v118, v118, v119
	v_add_f32_e32 v118, v120, v118
	v_fmamk_f32 v118, v118, 0x3a800000, v115
	v_rsq_f32_e32 v118, v118
	ds_write_b32 v116, v118 offset:10240
	s_cmp_lg_u32 s10, 1
	s_cbranch_scc1 .LBB0_470
	s_barrier

.LBB0_638:
	s_cmp_lt_i32 s74, 8
	s_cselect_b64 s[0:1], -1, 0
	s_cmp_gt_i32 s75, 7
	s_cselect_b64 s[4:5], -1, 0
	s_and_b64 s[0:1], s[0:1], s[4:5]
	s_andn2_b64 vcc, exec, s[0:1]
	s_cbranch_vccnz .LBB0_779
	v_lshlrev_b32_e32 v8, 2, v128
	s_ashr_i32 s3, s2, 31
	v_add_u32_e32 v0, 0, v8
	s_ashr_i32 s58, s72, 31
	s_mov_b32 s59, s72
	v_and_b32_e32 v4, 0xff, v128
	v_add_u32_e32 v5, 0xfffffe00, v128
	v_add_u32_e32 v6, 0x20000, v0
	v_lshrrev_b32_e32 v7, 8, v128
	s_mov_b64 s[0:1], 0
	s_waitcnt lgkmcnt(0)
	v_mov_b64_e32 v[0:1], s[2:3]
	s_mov_b64 s[4:5], 0x600
	s_mov_b32 s10, 0x2aaaaaab
	s_movk_i32 s11, 0x60
	v_mov_b32_e32 v9, 0x358637bd
	s_movk_i32 s12, 0x8ff
	v_mov_b32_e32 v10, 0xc0
	v_mov_b32_e32 v11, 0xc1
	v_and_b32_e32 v114, 0xff, v128
	s_lshr_b32 s98, s91, 2
	v_mov_b32_e32 v115, 0x358637bd
	s_mul_i32 s99, s98, s72
	s_add_i32 s99, s99, s2
	s_cmp_lt_u32 s99, 0x600
	s_cselect_b32 s99, s99, s2
	s_and_b32 s100, s99, 7
	s_mul_i32 s100, s100, 0xc0
	s_lshr_b32 s101, s99, 3
	s_add_i32 s100, s100, s101
	s_mul_hi_u32 s101, s100, 0x2aaaaab
	s_lshl_b32 s101, s101, 3
	s_and_b32 s100, s100, 7
	s_or_b32 s101, s101, s100
	s_lshl_b32 s101, s101, 8
	v_add_u32_e32 v112, s101, v114
	v_lshlrev_b32_e32 v112, 6, v112
	v_mov_b32_e32 v113, 0
	v_lshl_add_u64 v[112:113], s[18:19], 0, v[112:113]
	global_load_dwordx4 v[16:19], v[112:113], off
	global_load_dwordx4 v[20:23], v[112:113], off offset:16
	global_load_dwordx4 v[24:27], v[112:113], off offset:32
	global_load_dwordx4 v[28:31], v[112:113], off offset:48
	s_add_i32 s98, s98, 2
	s_mul_i32 s99, s98, s72
	s_add_i32 s99, s99, s2
	s_cmp_lt_u32 s99, 0x600
	s_cselect_b32 s99, s99, s2
	s_and_b32 s100, s99, 7
	s_mul_i32 s100, s100, 0xc0
	s_lshr_b32 s101, s99, 3
	s_add_i32 s100, s100, s101
	s_mul_hi_u32 s101, s100, 0x2aaaaab
	s_lshl_b32 s101, s101, 3
	s_and_b32 s100, s100, 7
	s_or_b32 s101, s101, s100
	s_lshl_b32 s101, s101, 8
	v_add_u32_e32 v112, s101, v114
	v_lshlrev_b32_e32 v112, 6, v112
	v_mov_b32_e32 v113, 0
	v_lshl_add_u64 v[112:113], s[18:19], 0, v[112:113]
	global_load_dwordx4 v[32:35], v[112:113], off
	global_load_dwordx4 v[36:39], v[112:113], off offset:16
	global_load_dwordx4 v[40:43], v[112:113], off offset:32
	global_load_dwordx4 v[44:47], v[112:113], off offset:48
	s_add_i32 s98, s98, 2
	s_mul_i32 s99, s98, s72
	s_add_i32 s99, s99, s2
	s_cmp_lt_u32 s99, 0x600
	s_cselect_b32 s99, s99, s2
	s_and_b32 s100, s99, 7
	s_mul_i32 s100, s100, 0xc0
	s_lshr_b32 s101, s99, 3
	s_add_i32 s100, s100, s101
	s_mul_hi_u32 s101, s100, 0x2aaaaab
	s_lshl_b32 s101, s101, 3
	s_and_b32 s100, s100, 7
	s_or_b32 s101, s101, s100
	s_lshl_b32 s101, s101, 8
	v_add_u32_e32 v112, s101, v114
	v_lshlrev_b32_e32 v112, 6, v112
	v_mov_b32_e32 v113, 0
	v_lshl_add_u64 v[112:113], s[18:19], 0, v[112:113]
	global_load_dwordx4 v[48:51], v[112:113], off
	global_load_dwordx4 v[52:55], v[112:113], off offset:16
	global_load_dwordx4 v[56:59], v[112:113], off offset:32
	global_load_dwordx4 v[60:63], v[112:113], off offset:48
	s_add_i32 s98, s98, 2
.LBB0_643:
	s_or_b64 exec, exec, s[0:1]
	s_cmpk_lt_i32 s2, 0x600
	s_cselect_b64 s[4:5], -1, 0
	s_cmpk_gt_i32 s2, 0x5ff
	v_readfirstlane_b32 s6, v128
	s_barrier
	s_cbranch_scc0 .LBB0_646
	s_andn2_b64 vcc, exec, s[4:5]
	s_cbranch_vccz .LBB0_647

.LBB0_647:
	v_lshrrev_b32_e32 v2, 1, v128
	v_lshrrev_b32_e32 v3, 5, v128
	v_and_b32_e32 v2, 24, v2
	v_and_b32_e32 v3, 4, v3
	v_bfe_u32 v4, v128, 2, 2
	v_lshlrev_b32_e32 v0, 4, v128
	v_and_b32_e32 v1, 32, v128
	v_bfe_u32 v11, v128, 2, 4
	v_or3_b32 v2, v3, v4, v2
	v_lshrrev_b32_e32 v3, 3, v128
	s_movk_i32 s1, 0x70
	s_lshr_b32 s4, s6, 6
	v_bitop3_b32 v9, v0, v1, 48 bitop3:0x6c
	v_and_b32_e32 v10, 64, v128
	v_and_or_b32 v4, v3, s1, v11
	s_movk_i32 s1, 0x60
	v_add_u32_e32 v12, 0x2000, v0
	v_or_b32_e32 v1, v9, v10
	v_and_or_b32 v3, v3, s1, v2
	v_lshrrev_b32_e32 v0, 7, v12
	s_movk_i32 s1, 0xf0
	s_lshr_b32 s7, s6, 8
	s_lshl_b32 s62, s4, 10
	v_lshl_or_b32 v134, v3, 11, v1
	v_and_or_b32 v3, v0, s1, v11
	s_movk_i32 s1, 0xe0
	s_add_u32 s63, s70, 0x1980000
	v_and_or_b32 v0, v0, s1, v2
	s_addc_u32 s64, s71, 0
	s_ashr_i32 s9, s8, 31
	s_ashr_i32 s1, s0, 31
	s_lshl_b64 s[10:11], s[8:9], 19
	s_lshl_b64 s[12:13], s[0:1], 19
	s_add_u32 s54, s63, s12
	s_addc_u32 s55, s64, s13
	s_add_i32 s65, s62, 0
	s_add_i32 m0, s65, 0x10000
	v_lshl_or_b32 v138, v0, 11, v1
	global_load_lds_dwordx4 v134, s[54:55]
	s_add_i32 m0, s65, 0x12000
	s_add_u32 s12, s54, 0x40000
	global_load_lds_dwordx4 v138, s[54:55]
	s_addc_u32 s13, s55, 0
	s_add_i32 m0, s65, 0x14000
	v_lshl_or_b32 v132, v4, 11, v1
	global_load_lds_dwordx4 v134, s[12:13]
	s_add_i32 m0, s65, 0x16000
	s_add_u32 s52, s14, s10
	s_addc_u32 s53, s15, s11
	s_add_i32 s66, s65, 0x2000
	global_load_lds_dwordx4 v138, s[12:13]
	s_mov_b32 m0, s65
	s_add_u32 s10, s52, 0x40000
	v_lshl_or_b32 v136, v3, 11, v1
	global_load_lds_dwordx4 v132, s[52:53]
	s_mov_b32 m0, s66
	s_addc_u32 s11, s53, 0
	s_add_i32 s67, s65, 0x4000
	global_load_lds_dwordx4 v136, s[52:53]
	s_mov_b32 m0, s67
	s_add_i32 s79, s65, 0x6000
	global_load_lds_dwordx4 v132, s[10:11]
	s_mov_b32 m0, s79
	v_writelane_b32 v238, s94, 4
	global_load_lds_dwordx4 v136, s[10:11]
	v_mov_b32_e32 v135, 0
	v_writelane_b32 v238, s95, 5
	v_mov_b32_e32 v139, v135
	v_mov_b32_e32 v133, v135
	v_mov_b32_e32 v137, v135
	s_cmp_eq_u32 s7, 1
	v_writelane_b32 v238, s92, 6
	s_mov_b32 s11, 0
	v_lshl_add_u64 v[6:7], s[54:55], 0, v[134:135]
	v_lshl_add_u64 v[4:5], s[54:55], 0, v[138:139]
	v_lshl_add_u64 v[0:1], s[52:53], 0, v[132:133]
	s_cselect_b64 s[22:23], -1, 0
	v_lshl_add_u64 v[2:3], s[52:53], 0, v[136:137]
	v_writelane_b32 v238, s93, 7
	s_add_u32 s81, s70, 0x1f900000
	s_mov_b64 s[26:27], 0x80
	s_addc_u32 s82, s71, 0
	s_and_b32 s1, s4, 3
	s_add_i32 m0, s65, 0x18000
	v_lshl_add_u64 v[6:7], v[6:7], 0, s[26:27]
	s_lshl_b32 s9, s7, 13
	s_lshl_b32 s10, s1, 12
	global_load_lds_dwordx4 v[6:7], off
	v_lshl_add_u64 v[4:5], v[4:5], 0, s[26:27]
	s_add_i32 m0, s65, 0x1a000
	s_add_i32 s83, s65, 0x8000
	s_add_i32 s84, s65, 0xa000
	global_load_lds_dwordx4 v[4:5], off
	v_lshl_add_u64 v[0:1], v[0:1], 0, s[26:27]
	s_mov_b32 m0, s83
	s_add_u32 s4, s54, 0x40080
	global_load_lds_dwordx4 v[0:1], off
	v_lshl_add_u64 v[0:1], v[2:3], 0, s[26:27]
	s_mov_b32 m0, s84
	s_addc_u32 s5, s55, 0
	global_load_lds_dwordx4 v[0:1], off
	s_add_i32 m0, s65, 0x1c000
	v_lshl_add_u64 v[0:1], s[4:5], 0, v[134:135]
	global_load_lds_dwordx4 v[0:1], off
	v_lshl_add_u64 v[0:1], s[4:5], 0, v[138:139]
	s_add_i32 m0, s65, 0x1e000
	global_load_lds_dwordx4 v[0:1], off
	v_lshlrev_b32_e32 v116, 2, v128
	v_add_u32_e32 v116, 0x20000, v116
	s_waitcnt vmcnt(22)
	v_pk_add_f32 v[118:119], v[18:19], v[22:23]
	v_pk_add_f32 v[120:121], v[16:17], v[20:21]
	v_pk_add_f32 v[122:123], v[26:27], v[30:31]
	v_pk_add_f32 v[124:125], v[24:25], v[28:29]
	v_pk_add_f32 v[118:119], v[118:119], v[122:123]
	v_pk_add_f32 v[120:121], v[120:121], v[124:125]
	v_add_f32_e32 v120, v121, v120
	v_add_f32_e32 v118, v118, v119
	v_add_f32_e32 v118, v120, v118
	v_fmamk_f32 v118, v118, 0x3a800000, v115
	v_rsq_f32_e32 v118, v118
	ds_write_b32 v116, v118
	s_waitcnt vmcnt(18)
	v_pk_add_f32 v[118:119], v[34:35], v[38:39]
	v_pk_add_f32 v[120:121], v[32:33], v[36:37]
	v_pk_add_f32 v[122:123], v[42:43], v[46:47]
	v_pk_add_f32 v[124:125], v[40:41], v[44:45]
	v_pk_add_f32 v[118:119], v[118:119], v[122:123]
	v_pk_add_f32 v[120:121], v[120:121], v[124:125]
	v_add_f32_e32 v120, v121, v120
	v_add_f32_e32 v118, v118, v119
	v_add_f32_e32 v118, v120, v118
	v_fmamk_f32 v118, v118, 0x3a800000, v115
	v_rsq_f32_e32 v118, v118
	ds_write_b32 v116, v118 offset:2048
	s_waitcnt vmcnt(14)
	v_pk_add_f32 v[118:119], v[50:51], v[54:55]
	v_pk_add_f32 v[120:121], v[48:49], v[52:53]
	v_pk_add_f32 v[122:123], v[58:59], v[62:63]
	v_pk_add_f32 v[124:125], v[56:57], v[60:61]
	v_pk_add_f32 v[118:119], v[118:119], v[122:123]
	v_pk_add_f32 v[120:121], v[120:121], v[124:125]
	v_add_f32_e32 v120, v121, v120
	v_add_f32_e32 v118, v118, v119
	v_add_f32_e32 v118, v120, v118
	v_fmamk_f32 v118, v118, 0x3a800000, v115
	v_rsq_f32_e32 v118, v118
	ds_write_b32 v116, v118 offset:4096
	s_cmp_lg_u32 s7, 1
	s_cbranch_scc1 .LBB0_649
	s_barrier

.LBB0_1045:
	s_cmp_lt_i32 s74, 11
	s_cselect_b64 s[0:1], -1, 0
	s_cmp_gt_i32 s75, 10
	s_cselect_b64 s[4:5], -1, 0
	s_and_b64 s[0:1], s[0:1], s[4:5]
	s_andn2_b64 vcc, exec, s[0:1]
	s_cbranch_vccnz .LBB0_1120
	v_lshlrev_b32_e32 v8, 2, v128
	s_ashr_i32 s3, s2, 31
	s_waitcnt vmcnt(0)
	v_add_u32_e32 v0, 0, v8
	s_ashr_i32 s42, s72, 31
	s_mov_b32 s43, s72
	v_and_b32_e32 v4, 0xff, v128
	v_add_u32_e32 v5, 0xfffffe00, v128
	v_add_u32_e32 v6, 0x20000, v0
	v_lshrrev_b32_e32 v7, 8, v128
	s_mov_b64 s[0:1], 0
	s_waitcnt lgkmcnt(0)
	v_mov_b64_e32 v[0:1], s[2:3]
	s_mov_b64 s[4:5], 0xb00
	s_mov_b32 s10, 0x2e8ba2e9
	s_movk_i32 s11, 0xb0
	v_mov_b32_e32 v9, 0x358637bd
	s_movk_i32 s12, 0x8ff
	v_mov_b32_e32 v10, 0x160
	v_mov_b32_e32 v11, 0x161
	v_and_b32_e32 v114, 0xff, v128
	s_lshr_b32 s98, s91, 2
	v_mov_b32_e32 v115, 0x358637bd
	s_mul_i32 s99, s98, s72
	s_add_i32 s99, s99, s2
	s_cmp_lt_u32 s99, 0xb00
	s_cselect_b32 s99, s99, s2
	s_and_b32 s100, s99, 7
	s_mul_i32 s100, s100, 0x160
	s_lshr_b32 s101, s99, 3
	s_add_i32 s100, s100, s101
	s_mul_hi_u32 s101, s100, 0x1745d18
	s_lshl_b32 s101, s101, 3
	s_and_b32 s100, s100, 7
	s_or_b32 s101, s101, s100
	s_lshl_b32 s101, s101, 8
	v_add_u32_e32 v112, s101, v114
	v_lshlrev_b32_e32 v112, 6, v112
	v_mov_b32_e32 v113, 0
	v_lshl_add_u64 v[112:113], s[18:19], 0, v[112:113]
	global_load_dwordx4 v[16:19], v[112:113], off
	global_load_dwordx4 v[20:23], v[112:113], off offset:16
	global_load_dwordx4 v[24:27], v[112:113], off offset:32
	global_load_dwordx4 v[28:31], v[112:113], off offset:48
	s_add_i32 s98, s98, 2
	s_mul_i32 s99, s98, s72
	s_add_i32 s99, s99, s2
	s_cmp_lt_u32 s99, 0xb00
	s_cselect_b32 s99, s99, s2
	s_and_b32 s100, s99, 7
	s_mul_i32 s100, s100, 0x160
	s_lshr_b32 s101, s99, 3
	s_add_i32 s100, s100, s101
	s_mul_hi_u32 s101, s100, 0x1745d18
	s_lshl_b32 s101, s101, 3
	s_and_b32 s100, s100, 7
	s_or_b32 s101, s101, s100
	s_lshl_b32 s101, s101, 8
	v_add_u32_e32 v112, s101, v114
	v_lshlrev_b32_e32 v112, 6, v112
	v_mov_b32_e32 v113, 0
	v_lshl_add_u64 v[112:113], s[18:19], 0, v[112:113]
	global_load_dwordx4 v[32:35], v[112:113], off
	global_load_dwordx4 v[36:39], v[112:113], off offset:16
	global_load_dwordx4 v[40:43], v[112:113], off offset:32
	global_load_dwordx4 v[44:47], v[112:113], off offset:48
	s_add_i32 s98, s98, 2
	s_mul_i32 s99, s98, s72
	s_add_i32 s99, s99, s2
	s_cmp_lt_u32 s99, 0xb00
	s_cselect_b32 s99, s99, s2
	s_and_b32 s100, s99, 7
	s_mul_i32 s100, s100, 0x160
	s_lshr_b32 s101, s99, 3
	s_add_i32 s100, s100, s101
	s_mul_hi_u32 s101, s100, 0x1745d18
	s_lshl_b32 s101, s101, 3
	s_and_b32 s100, s100, 7
	s_or_b32 s101, s101, s100
	s_lshl_b32 s101, s101, 8
	v_add_u32_e32 v112, s101, v114
	v_lshlrev_b32_e32 v112, 6, v112
	v_mov_b32_e32 v113, 0
	v_lshl_add_u64 v[112:113], s[18:19], 0, v[112:113]
	global_load_dwordx4 v[48:51], v[112:113], off
	global_load_dwordx4 v[52:55], v[112:113], off offset:16
	global_load_dwordx4 v[56:59], v[112:113], off offset:32
	global_load_dwordx4 v[60:63], v[112:113], off offset:48
	s_add_i32 s98, s98, 2
	s_mul_i32 s99, s98, s72
	s_add_i32 s99, s99, s2
	s_cmp_lt_u32 s99, 0xb00
	s_cselect_b32 s99, s99, s2
	s_and_b32 s100, s99, 7
	s_mul_i32 s100, s100, 0x160
	s_lshr_b32 s101, s99, 3
	s_add_i32 s100, s100, s101
	s_mul_hi_u32 s101, s100, 0x1745d18
	s_lshl_b32 s101, s101, 3
	s_and_b32 s100, s100, 7
	s_or_b32 s101, s101, s100
	s_lshl_b32 s101, s101, 8
	v_add_u32_e32 v112, s101, v114
	v_lshlrev_b32_e32 v112, 6, v112
	v_mov_b32_e32 v113, 0
	v_lshl_add_u64 v[112:113], s[18:19], 0, v[112:113]
	global_load_dwordx4 v[64:67], v[112:113], off
	global_load_dwordx4 v[68:71], v[112:113], off offset:16
	global_load_dwordx4 v[72:75], v[112:113], off offset:32
	global_load_dwordx4 v[76:79], v[112:113], off offset:48
	s_add_i32 s98, s98, 2
	s_mul_i32 s99, s98, s72
	s_add_i32 s99, s99, s2
	s_cmp_lt_u32 s99, 0xb00
	s_cselect_b32 s99, s99, s2
	s_and_b32 s100, s99, 7
	s_mul_i32 s100, s100, 0x160
	s_lshr_b32 s101, s99, 3
	s_add_i32 s100, s100, s101
	s_mul_hi_u32 s101, s100, 0x1745d18
	s_lshl_b32 s101, s101, 3
	s_and_b32 s100, s100, 7
	s_or_b32 s101, s101, s100
	s_lshl_b32 s101, s101, 8
	v_add_u32_e32 v112, s101, v114
	v_lshlrev_b32_e32 v112, 6, v112
	v_mov_b32_e32 v113, 0
	v_lshl_add_u64 v[112:113], s[18:19], 0, v[112:113]
	global_load_dwordx4 v[80:83], v[112:113], off
	global_load_dwordx4 v[84:87], v[112:113], off offset:16
	global_load_dwordx4 v[88:91], v[112:113], off offset:32
	global_load_dwordx4 v[92:95], v[112:113], off offset:48
	s_add_i32 s98, s98, 2
	s_mul_i32 s99, s98, s72
	s_add_i32 s99, s99, s2
	s_cmp_lt_u32 s99, 0xb00
	s_cselect_b32 s99, s99, s2
	s_and_b32 s100, s99, 7
	s_mul_i32 s100, s100, 0x160
	s_lshr_b32 s101, s99, 3
	s_add_i32 s100, s100, s101
	s_mul_hi_u32 s101, s100, 0x1745d18
	s_lshl_b32 s101, s101, 3
	s_and_b32 s100, s100, 7
	s_or_b32 s101, s101, s100
	s_lshl_b32 s101, s101, 8
	v_add_u32_e32 v112, s101, v114
	v_lshlrev_b32_e32 v112, 6, v112
	v_mov_b32_e32 v113, 0
	v_lshl_add_u64 v[112:113], s[18:19], 0, v[112:113]
	global_load_dwordx4 v[96:99], v[112:113], off
	global_load_dwordx4 v[100:103], v[112:113], off offset:16
	global_load_dwordx4 v[104:107], v[112:113], off offset:32
	global_load_dwordx4 v[108:111], v[112:113], off offset:48
	s_add_i32 s98, s98, 2
.LBB0_1050:
	s_or_b64 exec, exec, s[0:1]
	s_cmpk_gt_i32 s2, 0xaff
	v_readfirstlane_b32 s5, v128
	s_barrier
	s_cbranch_scc1 .LBB0_1066
	v_lshrrev_b32_e32 v0, 5, v128
	v_lshrrev_b32_e32 v2, 1, v128
	v_and_b32_e32 v0, 4, v0
	v_bfe_u32 v1, v128, 2, 2
	v_and_b32_e32 v12, 24, v2
	v_or3_b32 v0, v0, v1, v12
	v_lshlrev_b32_e32 v1, 4, v128
	v_add_u32_e32 v9, 0x2000, v1
	v_lshrrev_b32_e32 v2, 7, v9
	s_movk_i32 s0, 0xe0
	v_and_b32_e32 v4, 32, v128
	v_and_or_b32 v3, v2, s0, v0
	v_bitop3_b32 v10, v1, v4, 48 bitop3:0x6c
	v_and_b32_e32 v11, 64, v128
	v_bfe_u32 v13, v128, 2, 4
	s_movk_i32 s0, 0xf0
	s_lshr_b32 s6, s5, 6
	v_or_b32_e32 v1, v10, v11
	v_and_or_b32 v2, v2, s0, v13
	s_lshr_b32 s10, s5, 8
	s_lshl_b32 s48, s6, 10
	v_lshl_or_b32 v134, v2, 11, v1
	v_lshrrev_b32_e32 v2, 3, v128
	s_movk_i32 s0, 0x60
	s_add_u32 s49, s70, 0x2180000
	v_and_or_b32 v0, v2, s0, v0
	s_movk_i32 s0, 0x70
	s_addc_u32 s50, s71, 0
	v_lshl_or_b32 v136, v0, 11, v1
	v_and_or_b32 v0, v2, s0, v13
	s_lshr_b32 s0, s3, 29
	s_add_i32 s0, s2, s0
	s_ashr_i32 s1, s0, 3
	s_and_b32 s0, s0, -8
	s_sub_i32 s0, s2, s0
	s_cmp_lt_i32 s0, 0
	s_movk_i32 s51, 0x161
	s_cselect_b32 s4, s51, 0x160
	s_mul_i32 s0, s0, s4
	s_add_i32 s0, s0, s1
	s_mul_hi_i32 s1, s0, 0x2e8ba2e9
	s_lshr_b32 s4, s1, 31
	s_ashr_i32 s1, s1, 5
	s_add_i32 s1, s1, s4
	s_lshl_b32 s7, s1, 3
	s_mulk_i32 s1, 0xb0
	s_sub_i32 s0, s0, s1
	s_bfe_u32 s1, s0, 0x3001c
	s_add_i32 s1, s0, s1
	s_sext_i32_i16 s4, s1
	s_and_b32 s1, s1, 0xfff8
	s_sub_i32 s0, s0, s1
	s_sext_i32_i16 s0, s0
	s_lshr_b32 s4, s4, 3
	s_add_i32 s30, s7, s0
	s_ashr_i32 s31, s30, 31
	s_bfe_i64 s[8:9], s[4:5], 0x100000
	s_lshl_b64 s[0:1], s[30:31], 19
	s_lshl_b64 s[8:9], s[8:9], 19
	s_add_u32 s38, s49, s8
	s_addc_u32 s39, s50, s9
	s_add_i32 s31, s48, 0
	s_add_i32 m0, s31, 0x10000
	v_lshl_or_b32 v132, v3, 11, v1
	global_load_lds_dwordx4 v136, s[38:39]
	s_add_i32 m0, s31, 0x12000
	s_add_u32 s8, s38, 0x40000
	global_load_lds_dwordx4 v132, s[38:39]
	s_addc_u32 s9, s39, 0
	s_add_i32 m0, s31, 0x14000
	v_lshl_or_b32 v138, v0, 11, v1
	global_load_lds_dwordx4 v136, s[8:9]
	s_add_i32 m0, s31, 0x16000
	s_add_u32 s36, s14, s0
	s_addc_u32 s37, s15, s1
	s_add_i32 s52, s31, 0x2000
	global_load_lds_dwordx4 v132, s[8:9]
	s_mov_b32 m0, s31
	s_add_u32 s0, s36, 0x40000
	global_load_lds_dwordx4 v138, s[36:37]
	s_mov_b32 m0, s52
	s_addc_u32 s1, s37, 0
	s_add_i32 s53, s31, 0x4000
	global_load_lds_dwordx4 v134, s[36:37]
	s_mov_b32 m0, s53
	s_add_i32 s54, s31, 0x6000
	global_load_lds_dwordx4 v138, s[0:1]
	s_mov_b32 m0, s54
	v_mov_b32_e32 v137, 0
	global_load_lds_dwordx4 v134, s[0:1]
	v_mov_b32_e32 v133, v137
	v_mov_b32_e32 v139, v137
	v_mov_b32_e32 v135, v137
	s_cmp_eq_u32 s10, 1
	s_mov_b32 s12, 0
	v_lshl_add_u64 v[6:7], s[38:39], 0, v[136:137]
	v_lshl_add_u64 v[4:5], s[38:39], 0, v[132:133]
	v_lshl_add_u64 v[0:1], s[36:37], 0, v[138:139]
	s_cselect_b64 s[0:1], -1, 0
	v_lshl_add_u64 v[2:3], s[36:37], 0, v[134:135]
	s_lshl_b32 s6, s6, 5
	s_and_b32 s22, s6, 0x60
	s_mov_b64 s[6:7], 0x80
	s_add_i32 m0, s31, 0x18000
	v_lshl_add_u64 v[6:7], v[6:7], 0, s[6:7]
	s_lshl_b32 s11, s10, 13
	s_lshl_b32 s23, s22, 7
	global_load_lds_dwordx4 v[6:7], off
	v_lshl_add_u64 v[4:5], v[4:5], 0, s[6:7]
	s_add_i32 m0, s31, 0x1a000
	s_add_i32 s55, s31, 0x8000
	s_add_i32 s56, s31, 0xa000
	global_load_lds_dwordx4 v[4:5], off
	v_lshl_add_u64 v[0:1], v[0:1], 0, s[6:7]
	s_mov_b32 m0, s55
	s_add_u32 s8, s38, 0x40080
	global_load_lds_dwordx4 v[0:1], off
	v_lshl_add_u64 v[0:1], v[2:3], 0, s[6:7]
	s_mov_b32 m0, s56
	s_addc_u32 s9, s39, 0
	global_load_lds_dwordx4 v[0:1], off
	s_add_i32 m0, s31, 0x1c000
	v_lshl_add_u64 v[0:1], s[8:9], 0, v[136:137]
	global_load_lds_dwordx4 v[0:1], off
	v_lshl_add_u64 v[0:1], s[8:9], 0, v[132:133]
	s_add_i32 m0, s31, 0x1e000
	s_sext_i32_i16 s13, s4
	global_load_lds_dwordx4 v[0:1], off
	v_lshlrev_b32_e32 v116, 2, v128
	v_add_u32_e32 v116, 0x20000, v116
	s_waitcnt vmcnt(34)
	v_pk_add_f32 v[118:119], v[18:19], v[22:23]
	v_pk_add_f32 v[120:121], v[16:17], v[20:21]
	v_pk_add_f32 v[122:123], v[26:27], v[30:31]
	v_pk_add_f32 v[124:125], v[24:25], v[28:29]
	v_pk_add_f32 v[118:119], v[118:119], v[122:123]
	v_pk_add_f32 v[120:121], v[120:121], v[124:125]
	v_add_f32_e32 v120, v121, v120
	v_add_f32_e32 v118, v118, v119
	v_add_f32_e32 v118, v120, v118
	v_fmamk_f32 v118, v118, 0x3a800000, v115
	v_rsq_f32_e32 v118, v118
	ds_write_b32 v116, v118
	s_waitcnt vmcnt(30)
	v_pk_add_f32 v[118:119], v[34:35], v[38:39]
	v_pk_add_f32 v[120:121], v[32:33], v[36:37]
	v_pk_add_f32 v[122:123], v[42:43], v[46:47]
	v_pk_add_f32 v[124:125], v[40:41], v[44:45]
	v_pk_add_f32 v[118:119], v[118:119], v[122:123]
	v_pk_add_f32 v[120:121], v[120:121], v[124:125]
	v_add_f32_e32 v120, v121, v120
	v_add_f32_e32 v118, v118, v119
	v_add_f32_e32 v118, v120, v118
	v_fmamk_f32 v118, v118, 0x3a800000, v115
	v_rsq_f32_e32 v118, v118
	ds_write_b32 v116, v118 offset:2048
	s_waitcnt vmcnt(26)
	v_pk_add_f32 v[118:119], v[50:51], v[54:55]
	v_pk_add_f32 v[120:121], v[48:49], v[52:53]
	v_pk_add_f32 v[122:123], v[58:59], v[62:63]
	v_pk_add_f32 v[124:125], v[56:57], v[60:61]
	v_pk_add_f32 v[118:119], v[118:119], v[122:123]
	v_pk_add_f32 v[120:121], v[120:121], v[124:125]
	v_add_f32_e32 v120, v121, v120
	v_add_f32_e32 v118, v118, v119
	v_add_f32_e32 v118, v120, v118
	v_fmamk_f32 v118, v118, 0x3a800000, v115
	v_rsq_f32_e32 v118, v118
	ds_write_b32 v116, v118 offset:4096
	s_waitcnt vmcnt(22)
	v_pk_add_f32 v[118:119], v[66:67], v[70:71]
	v_pk_add_f32 v[120:121], v[64:65], v[68:69]
	v_pk_add_f32 v[122:123], v[74:75], v[78:79]
	v_pk_add_f32 v[124:125], v[72:73], v[76:77]
	v_pk_add_f32 v[118:119], v[118:119], v[122:123]
	v_pk_add_f32 v[120:121], v[120:121], v[124:125]
	v_add_f32_e32 v120, v121, v120
	v_add_f32_e32 v118, v118, v119
	v_add_f32_e32 v118, v120, v118
	v_fmamk_f32 v118, v118, 0x3a800000, v115
	v_rsq_f32_e32 v118, v118
	ds_write_b32 v116, v118 offset:6144
	s_waitcnt vmcnt(18)
	v_pk_add_f32 v[118:119], v[82:83], v[86:87]
	v_pk_add_f32 v[120:121], v[80:81], v[84:85]
	v_pk_add_f32 v[122:123], v[90:91], v[94:95]
	v_pk_add_f32 v[124:125], v[88:89], v[92:93]
	v_pk_add_f32 v[118:119], v[118:119], v[122:123]
	v_pk_add_f32 v[120:121], v[120:121], v[124:125]
	v_add_f32_e32 v120, v121, v120
	v_add_f32_e32 v118, v118, v119
	v_add_f32_e32 v118, v120, v118
	v_fmamk_f32 v118, v118, 0x3a800000, v115
	v_rsq_f32_e32 v118, v118
	ds_write_b32 v116, v118 offset:8192
	s_waitcnt vmcnt(14)
	v_pk_add_f32 v[118:119], v[98:99], v[102:103]
	v_pk_add_f32 v[120:121], v[96:97], v[100:101]
	v_pk_add_f32 v[122:123], v[106:107], v[110:111]
	v_pk_add_f32 v[124:125], v[104:105], v[108:109]
	v_pk_add_f32 v[118:119], v[118:119], v[122:123]
	v_pk_add_f32 v[120:121], v[120:121], v[124:125]
	v_add_f32_e32 v120, v121, v120
	v_add_f32_e32 v118, v118, v119
	v_add_f32_e32 v118, v120, v118
	v_fmamk_f32 v118, v118, 0x3a800000, v115
	v_rsq_f32_e32 v118, v118
	ds_write_b32 v116, v118 offset:10240
	s_cmp_lg_u32 s10, 1
	s_cbranch_scc1 .LBB0_1053
	s_barrier

.LBB0_1221:
	s_cmp_lt_i32 s74, 13
	s_cselect_b64 s[0:1], -1, 0
	s_cmp_gt_i32 s75, 12
	s_cselect_b64 s[4:5], -1, 0
	s_and_b64 s[0:1], s[0:1], s[4:5]
	s_andn2_b64 vcc, exec, s[0:1]
	s_cbranch_vccnz .LBB0_1296
	v_lshlrev_b32_e32 v8, 2, v128
	s_ashr_i32 s3, s2, 31
	s_waitcnt vmcnt(0)
	v_add_u32_e32 v0, 0, v8
	s_ashr_i32 s42, s72, 31
	s_mov_b32 s43, s72
	v_and_b32_e32 v4, 0xff, v128
	v_add_u32_e32 v5, 0xfffffe00, v128
	v_add_u32_e32 v6, 0x20000, v0
	v_lshrrev_b32_e32 v7, 8, v128
	s_mov_b64 s[0:1], 0
	s_waitcnt lgkmcnt(0)
	v_mov_b64_e32 v[0:1], s[2:3]
	s_mov_b64 s[4:5], 0x600
	s_mov_b32 s10, 0x2aaaaaab
	s_movk_i32 s11, 0x60
	v_mov_b32_e32 v9, 0x358637bd
	s_movk_i32 s12, 0x8ff
	v_mov_b32_e32 v10, 0xc0
	v_mov_b32_e32 v11, 0xc1
	v_and_b32_e32 v114, 0xff, v128
	s_lshr_b32 s98, s91, 2
	v_mov_b32_e32 v115, 0x358637bd
	s_mul_i32 s99, s98, s72
	s_add_i32 s99, s99, s2
	s_cmp_lt_u32 s99, 0x600
	s_cselect_b32 s99, s99, s2
	s_and_b32 s100, s99, 7
	s_mul_i32 s100, s100, 0xc0
	s_lshr_b32 s101, s99, 3
	s_add_i32 s100, s100, s101
	s_mul_hi_u32 s101, s100, 0x2aaaaab
	s_lshl_b32 s101, s101, 3
	s_and_b32 s100, s100, 7
	s_or_b32 s101, s101, s100
	s_lshl_b32 s101, s101, 8
	v_add_u32_e32 v112, s101, v114
	v_lshlrev_b32_e32 v112, 6, v112
	v_mov_b32_e32 v113, 0
	v_lshl_add_u64 v[112:113], s[18:19], 0, v[112:113]
	global_load_dwordx4 v[16:19], v[112:113], off
	global_load_dwordx4 v[20:23], v[112:113], off offset:16
	global_load_dwordx4 v[24:27], v[112:113], off offset:32
	global_load_dwordx4 v[28:31], v[112:113], off offset:48
	s_add_i32 s98, s98, 2
	s_mul_i32 s99, s98, s72
	s_add_i32 s99, s99, s2
	s_cmp_lt_u32 s99, 0x600
	s_cselect_b32 s99, s99, s2
	s_and_b32 s100, s99, 7
	s_mul_i32 s100, s100, 0xc0
	s_lshr_b32 s101, s99, 3
	s_add_i32 s100, s100, s101
	s_mul_hi_u32 s101, s100, 0x2aaaaab
	s_lshl_b32 s101, s101, 3
	s_and_b32 s100, s100, 7
	s_or_b32 s101, s101, s100
	s_lshl_b32 s101, s101, 8
	v_add_u32_e32 v112, s101, v114
	v_lshlrev_b32_e32 v112, 6, v112
	v_mov_b32_e32 v113, 0
	v_lshl_add_u64 v[112:113], s[18:19], 0, v[112:113]
	global_load_dwordx4 v[32:35], v[112:113], off
	global_load_dwordx4 v[36:39], v[112:113], off offset:16
	global_load_dwordx4 v[40:43], v[112:113], off offset:32
	global_load_dwordx4 v[44:47], v[112:113], off offset:48
	s_add_i32 s98, s98, 2
	s_mul_i32 s99, s98, s72
	s_add_i32 s99, s99, s2
	s_cmp_lt_u32 s99, 0x600
	s_cselect_b32 s99, s99, s2
	s_and_b32 s100, s99, 7
	s_mul_i32 s100, s100, 0xc0
	s_lshr_b32 s101, s99, 3
	s_add_i32 s100, s100, s101
	s_mul_hi_u32 s101, s100, 0x2aaaaab
	s_lshl_b32 s101, s101, 3
	s_and_b32 s100, s100, 7
	s_or_b32 s101, s101, s100
	s_lshl_b32 s101, s101, 8
	v_add_u32_e32 v112, s101, v114
	v_lshlrev_b32_e32 v112, 6, v112
	v_mov_b32_e32 v113, 0
	v_lshl_add_u64 v[112:113], s[18:19], 0, v[112:113]
	global_load_dwordx4 v[48:51], v[112:113], off
	global_load_dwordx4 v[52:55], v[112:113], off offset:16
	global_load_dwordx4 v[56:59], v[112:113], off offset:32
	global_load_dwordx4 v[60:63], v[112:113], off offset:48
	s_add_i32 s98, s98, 2
.LBB0_1226:
	s_or_b64 exec, exec, s[0:1]
	s_cmpk_gt_i32 s2, 0x5ff
	v_readfirstlane_b32 s5, v128
	s_barrier
	s_cbranch_scc1 .LBB0_1242
	v_lshrrev_b32_e32 v0, 5, v128
	v_lshrrev_b32_e32 v2, 1, v128
	v_and_b32_e32 v0, 4, v0
	v_bfe_u32 v1, v128, 2, 2
	v_and_b32_e32 v12, 24, v2
	v_or3_b32 v0, v0, v1, v12
	v_lshlrev_b32_e32 v1, 4, v128
	v_add_u32_e32 v9, 0x2000, v1
	v_lshrrev_b32_e32 v2, 7, v9
	s_movk_i32 s0, 0xe0
	v_and_b32_e32 v4, 32, v128
	v_and_or_b32 v3, v2, s0, v0
	v_bitop3_b32 v10, v1, v4, 48 bitop3:0x6c
	v_and_b32_e32 v11, 64, v128
	v_bfe_u32 v13, v128, 2, 4
	s_movk_i32 s0, 0xf0
	s_lshr_b32 s6, s5, 6
	v_or_b32_e32 v1, v10, v11
	v_and_or_b32 v2, v2, s0, v13
	s_lshr_b32 s10, s5, 8
	s_lshl_b32 s48, s6, 10
	v_lshl_or_b32 v134, v2, 11, v1
	v_lshrrev_b32_e32 v2, 3, v128
	s_movk_i32 s0, 0x60
	s_add_u32 s49, s70, 0x3200000
	v_and_or_b32 v0, v2, s0, v0
	s_movk_i32 s0, 0x70
	s_addc_u32 s50, s71, 0
	v_lshl_or_b32 v136, v0, 11, v1
	v_and_or_b32 v0, v2, s0, v13
	s_lshr_b32 s0, s3, 29
	s_add_i32 s0, s2, s0
	s_ashr_i32 s1, s0, 3
	s_and_b32 s0, s0, -8
	s_sub_i32 s0, s2, s0
	s_cmp_lt_i32 s0, 0
	s_movk_i32 s51, 0xc1
	s_cselect_b32 s4, s51, 0xc0
	s_mul_i32 s0, s0, s4
	s_add_i32 s0, s0, s1
	s_mul_hi_i32 s1, s0, 0x2aaaaaab
	s_lshr_b32 s4, s1, 31
	s_ashr_i32 s1, s1, 4
	s_add_i32 s1, s1, s4
	s_lshl_b32 s7, s1, 3
	s_mulk_i32 s1, 0x60
	s_sub_i32 s0, s0, s1
	s_bfe_i32 s1, s0, 0x80000
	s_bfe_u32 s1, s1, 0x3000c
	s_add_i32 s1, s0, s1
	s_bfe_i32 s4, s1, 0x80000
	s_and_b32 s1, s1, 0xf8
	s_sub_i32 s0, s0, s1
	s_sext_i32_i16 s4, s4
	s_sext_i32_i8 s0, s0
	s_lshr_b32 s4, s4, 3
	s_add_i32 s30, s7, s0
	s_ashr_i32 s31, s30, 31
	s_bfe_i64 s[8:9], s[4:5], 0x100000
	s_lshl_b64 s[0:1], s[30:31], 19
	s_lshl_b64 s[8:9], s[8:9], 19
	s_add_u32 s38, s49, s8
	s_addc_u32 s39, s50, s9
	s_add_i32 s31, s48, 0
	s_add_i32 m0, s31, 0x10000
	v_lshl_or_b32 v132, v3, 11, v1
	global_load_lds_dwordx4 v136, s[38:39]
	s_add_i32 m0, s31, 0x12000
	s_add_u32 s8, s38, 0x40000
	global_load_lds_dwordx4 v132, s[38:39]
	s_addc_u32 s9, s39, 0
	s_add_i32 m0, s31, 0x14000
	v_lshl_or_b32 v138, v0, 11, v1
	global_load_lds_dwordx4 v136, s[8:9]
	s_add_i32 m0, s31, 0x16000
	s_add_u32 s36, s14, s0
	s_addc_u32 s37, s15, s1
	s_add_i32 s52, s31, 0x2000
	global_load_lds_dwordx4 v132, s[8:9]
	s_mov_b32 m0, s31
	s_add_u32 s0, s36, 0x40000
	global_load_lds_dwordx4 v138, s[36:37]
	s_mov_b32 m0, s52
	s_addc_u32 s1, s37, 0
	s_add_i32 s53, s31, 0x4000
	global_load_lds_dwordx4 v134, s[36:37]
	s_mov_b32 m0, s53
	s_add_i32 s54, s31, 0x6000
	global_load_lds_dwordx4 v138, s[0:1]
	s_mov_b32 m0, s54
	v_mov_b32_e32 v137, 0
	global_load_lds_dwordx4 v134, s[0:1]
	v_mov_b32_e32 v133, v137
	v_mov_b32_e32 v139, v137
	v_mov_b32_e32 v135, v137
	s_cmp_eq_u32 s10, 1
	s_mov_b32 s62, 0
	v_lshl_add_u64 v[6:7], s[38:39], 0, v[136:137]
	v_lshl_add_u64 v[4:5], s[38:39], 0, v[132:133]
	v_lshl_add_u64 v[0:1], s[36:37], 0, v[138:139]
	s_cselect_b64 s[0:1], -1, 0
	v_lshl_add_u64 v[2:3], s[36:37], 0, v[134:135]
	s_lshl_b32 s6, s6, 5
	s_and_b32 s22, s6, 0x60
	s_mov_b64 s[6:7], 0x80
	s_add_i32 m0, s31, 0x18000
	v_lshl_add_u64 v[6:7], v[6:7], 0, s[6:7]
	s_lshl_b32 s11, s10, 13
	s_lshl_b32 s23, s22, 7
	global_load_lds_dwordx4 v[6:7], off
	v_lshl_add_u64 v[4:5], v[4:5], 0, s[6:7]
	s_add_i32 m0, s31, 0x1a000
	s_add_i32 s12, s31, 0x8000
	s_add_i32 s13, s31, 0xa000
	global_load_lds_dwordx4 v[4:5], off
	v_lshl_add_u64 v[0:1], v[0:1], 0, s[6:7]
	s_mov_b32 m0, s12
	s_add_u32 s8, s38, 0x40080
	global_load_lds_dwordx4 v[0:1], off
	v_lshl_add_u64 v[0:1], v[2:3], 0, s[6:7]
	s_mov_b32 m0, s13
	s_addc_u32 s9, s39, 0
	global_load_lds_dwordx4 v[0:1], off
	s_add_i32 m0, s31, 0x1c000
	v_lshl_add_u64 v[0:1], s[8:9], 0, v[136:137]
	global_load_lds_dwordx4 v[0:1], off
	v_lshl_add_u64 v[0:1], s[8:9], 0, v[132:133]
	s_add_i32 m0, s31, 0x1e000
	s_sext_i32_i8 s63, s4
	global_load_lds_dwordx4 v[0:1], off
	v_lshlrev_b32_e32 v116, 2, v128
	v_add_u32_e32 v116, 0x20000, v116
	s_waitcnt vmcnt(22)
	v_pk_add_f32 v[118:119], v[18:19], v[22:23]
	v_pk_add_f32 v[120:121], v[16:17], v[20:21]
	v_pk_add_f32 v[122:123], v[26:27], v[30:31]
	v_pk_add_f32 v[124:125], v[24:25], v[28:29]
	v_pk_add_f32 v[118:119], v[118:119], v[122:123]
	v_pk_add_f32 v[120:121], v[120:121], v[124:125]
	v_add_f32_e32 v120, v121, v120
	v_add_f32_e32 v118, v118, v119
	v_add_f32_e32 v118, v120, v118
	v_fmamk_f32 v118, v118, 0x3a800000, v115
	v_rsq_f32_e32 v118, v118
	ds_write_b32 v116, v118
	s_waitcnt vmcnt(18)
	v_pk_add_f32 v[118:119], v[34:35], v[38:39]
	v_pk_add_f32 v[120:121], v[32:33], v[36:37]
	v_pk_add_f32 v[122:123], v[42:43], v[46:47]
	v_pk_add_f32 v[124:125], v[40:41], v[44:45]
	v_pk_add_f32 v[118:119], v[118:119], v[122:123]
	v_pk_add_f32 v[120:121], v[120:121], v[124:125]
	v_add_f32_e32 v120, v121, v120
	v_add_f32_e32 v118, v118, v119
	v_add_f32_e32 v118, v120, v118
	v_fmamk_f32 v118, v118, 0x3a800000, v115
	v_rsq_f32_e32 v118, v118
	ds_write_b32 v116, v118 offset:2048
	s_waitcnt vmcnt(14)
	v_pk_add_f32 v[118:119], v[50:51], v[54:55]
	v_pk_add_f32 v[120:121], v[48:49], v[52:53]
	v_pk_add_f32 v[122:123], v[58:59], v[62:63]
	v_pk_add_f32 v[124:125], v[56:57], v[60:61]
	v_pk_add_f32 v[118:119], v[118:119], v[122:123]
	v_pk_add_f32 v[120:121], v[120:121], v[124:125]
	v_add_f32_e32 v120, v121, v120
	v_add_f32_e32 v118, v118, v119
	v_add_f32_e32 v118, v120, v118
	v_fmamk_f32 v118, v118, 0x3a800000, v115
	v_rsq_f32_e32 v118, v118
	ds_write_b32 v116, v118 offset:4096
	s_cmp_lg_u32 s10, 1
	s_cbranch_scc1 .LBB0_1229
	s_barrier

.LBB0_1633:
	s_cmp_lt_i32 s74, 18
	s_cselect_b64 s[0:1], -1, 0
	s_cmp_gt_i32 s75, 17
	s_cselect_b64 s[4:5], -1, 0
	s_and_b64 s[0:1], s[0:1], s[4:5]
	s_andn2_b64 vcc, exec, s[0:1]
	s_cbranch_vccnz .LBB0_1708
	s_waitcnt vmcnt(0)
	v_lshlrev_b32_e32 v8, 2, v128
	s_ashr_i32 s3, s2, 31
	v_add_u32_e32 v0, 0, v8
	s_ashr_i32 s42, s72, 31
	s_mov_b32 s43, s72
	v_and_b32_e32 v4, 0xff, v128
	v_add_u32_e32 v5, 0xfffffe00, v128
	v_add_u32_e32 v6, 0x20000, v0
	v_lshrrev_b32_e32 v7, 8, v128
	s_mov_b64 s[0:1], 0
	s_waitcnt lgkmcnt(0)
	v_mov_b64_e32 v[0:1], s[2:3]
	s_mov_b64 s[4:5], 0xb00
	s_mov_b32 s10, 0x2e8ba2e9
	s_movk_i32 s11, 0xb0
	v_mov_b32_e32 v9, 0x358637bd
	s_movk_i32 s12, 0x8ff
	v_mov_b32_e32 v10, 0x160
	v_mov_b32_e32 v11, 0x161
	v_and_b32_e32 v114, 0xff, v128
	s_lshr_b32 s98, s91, 2
	v_mov_b32_e32 v115, 0x358637bd
	s_mul_i32 s99, s98, s72
	s_add_i32 s99, s99, s2
	s_cmp_lt_u32 s99, 0xb00
	s_cselect_b32 s99, s99, s2
	s_and_b32 s100, s99, 7
	s_mul_i32 s100, s100, 0x160
	s_lshr_b32 s101, s99, 3
	s_add_i32 s100, s100, s101
	s_mul_hi_u32 s101, s100, 0x1745d18
	s_lshl_b32 s101, s101, 3
	s_and_b32 s100, s100, 7
	s_or_b32 s101, s101, s100
	s_lshl_b32 s101, s101, 8
	v_add_u32_e32 v112, s101, v114
	v_lshlrev_b32_e32 v112, 6, v112
	v_mov_b32_e32 v113, 0
	v_lshl_add_u64 v[112:113], s[18:19], 0, v[112:113]
	global_load_dwordx4 v[16:19], v[112:113], off
	global_load_dwordx4 v[20:23], v[112:113], off offset:16
	global_load_dwordx4 v[24:27], v[112:113], off offset:32
	global_load_dwordx4 v[28:31], v[112:113], off offset:48
	s_add_i32 s98, s98, 2
	s_mul_i32 s99, s98, s72
	s_add_i32 s99, s99, s2
	s_cmp_lt_u32 s99, 0xb00
	s_cselect_b32 s99, s99, s2
	s_and_b32 s100, s99, 7
	s_mul_i32 s100, s100, 0x160
	s_lshr_b32 s101, s99, 3
	s_add_i32 s100, s100, s101
	s_mul_hi_u32 s101, s100, 0x1745d18
	s_lshl_b32 s101, s101, 3
	s_and_b32 s100, s100, 7
	s_or_b32 s101, s101, s100
	s_lshl_b32 s101, s101, 8
	v_add_u32_e32 v112, s101, v114
	v_lshlrev_b32_e32 v112, 6, v112
	v_mov_b32_e32 v113, 0
	v_lshl_add_u64 v[112:113], s[18:19], 0, v[112:113]
	global_load_dwordx4 v[32:35], v[112:113], off
	global_load_dwordx4 v[36:39], v[112:113], off offset:16
	global_load_dwordx4 v[40:43], v[112:113], off offset:32
	global_load_dwordx4 v[44:47], v[112:113], off offset:48
	s_add_i32 s98, s98, 2
	s_mul_i32 s99, s98, s72
	s_add_i32 s99, s99, s2
	s_cmp_lt_u32 s99, 0xb00
	s_cselect_b32 s99, s99, s2
	s_and_b32 s100, s99, 7
	s_mul_i32 s100, s100, 0x160
	s_lshr_b32 s101, s99, 3
	s_add_i32 s100, s100, s101
	s_mul_hi_u32 s101, s100, 0x1745d18
	s_lshl_b32 s101, s101, 3
	s_and_b32 s100, s100, 7
	s_or_b32 s101, s101, s100
	s_lshl_b32 s101, s101, 8
	v_add_u32_e32 v112, s101, v114
	v_lshlrev_b32_e32 v112, 6, v112
	v_mov_b32_e32 v113, 0
	v_lshl_add_u64 v[112:113], s[18:19], 0, v[112:113]
	global_load_dwordx4 v[48:51], v[112:113], off
	global_load_dwordx4 v[52:55], v[112:113], off offset:16
	global_load_dwordx4 v[56:59], v[112:113], off offset:32
	global_load_dwordx4 v[60:63], v[112:113], off offset:48
	s_add_i32 s98, s98, 2
	s_mul_i32 s99, s98, s72
	s_add_i32 s99, s99, s2
	s_cmp_lt_u32 s99, 0xb00
	s_cselect_b32 s99, s99, s2
	s_and_b32 s100, s99, 7
	s_mul_i32 s100, s100, 0x160
	s_lshr_b32 s101, s99, 3
	s_add_i32 s100, s100, s101
	s_mul_hi_u32 s101, s100, 0x1745d18
	s_lshl_b32 s101, s101, 3
	s_and_b32 s100, s100, 7
	s_or_b32 s101, s101, s100
	s_lshl_b32 s101, s101, 8
	v_add_u32_e32 v112, s101, v114
	v_lshlrev_b32_e32 v112, 6, v112
	v_mov_b32_e32 v113, 0
	v_lshl_add_u64 v[112:113], s[18:19], 0, v[112:113]
	global_load_dwordx4 v[64:67], v[112:113], off
	global_load_dwordx4 v[68:71], v[112:113], off offset:16
	global_load_dwordx4 v[72:75], v[112:113], off offset:32
	global_load_dwordx4 v[76:79], v[112:113], off offset:48
	s_add_i32 s98, s98, 2
	s_mul_i32 s99, s98, s72
	s_add_i32 s99, s99, s2
	s_cmp_lt_u32 s99, 0xb00
	s_cselect_b32 s99, s99, s2
	s_and_b32 s100, s99, 7
	s_mul_i32 s100, s100, 0x160
	s_lshr_b32 s101, s99, 3
	s_add_i32 s100, s100, s101
	s_mul_hi_u32 s101, s100, 0x1745d18
	s_lshl_b32 s101, s101, 3
	s_and_b32 s100, s100, 7
	s_or_b32 s101, s101, s100
	s_lshl_b32 s101, s101, 8
	v_add_u32_e32 v112, s101, v114
	v_lshlrev_b32_e32 v112, 6, v112
	v_mov_b32_e32 v113, 0
	v_lshl_add_u64 v[112:113], s[18:19], 0, v[112:113]
	global_load_dwordx4 v[80:83], v[112:113], off
	global_load_dwordx4 v[84:87], v[112:113], off offset:16
	global_load_dwordx4 v[88:91], v[112:113], off offset:32
	global_load_dwordx4 v[92:95], v[112:113], off offset:48
	s_add_i32 s98, s98, 2
	s_mul_i32 s99, s98, s72
	s_add_i32 s99, s99, s2
	s_cmp_lt_u32 s99, 0xb00
	s_cselect_b32 s99, s99, s2
	s_and_b32 s100, s99, 7
	s_mul_i32 s100, s100, 0x160
	s_lshr_b32 s101, s99, 3
	s_add_i32 s100, s100, s101
	s_mul_hi_u32 s101, s100, 0x1745d18
	s_lshl_b32 s101, s101, 3
	s_and_b32 s100, s100, 7
	s_or_b32 s101, s101, s100
	s_lshl_b32 s101, s101, 8
	v_add_u32_e32 v112, s101, v114
	v_lshlrev_b32_e32 v112, 6, v112
	v_mov_b32_e32 v113, 0
	v_lshl_add_u64 v[112:113], s[18:19], 0, v[112:113]
	global_load_dwordx4 v[96:99], v[112:113], off
	global_load_dwordx4 v[100:103], v[112:113], off offset:16
	global_load_dwordx4 v[104:107], v[112:113], off offset:32
	global_load_dwordx4 v[108:111], v[112:113], off offset:48
	s_add_i32 s98, s98, 2
.LBB0_1638:
	s_or_b64 exec, exec, s[0:1]
	s_cmpk_gt_i32 s2, 0xaff
	v_readfirstlane_b32 s5, v128
	s_barrier
	s_cbranch_scc1 .LBB0_1654
	v_lshrrev_b32_e32 v0, 5, v128
	v_lshrrev_b32_e32 v2, 1, v128
	v_and_b32_e32 v0, 4, v0
	v_bfe_u32 v1, v128, 2, 2
	v_and_b32_e32 v12, 24, v2
	v_or3_b32 v0, v0, v1, v12
	v_lshlrev_b32_e32 v1, 4, v128
	v_add_u32_e32 v9, 0x2000, v1
	v_lshrrev_b32_e32 v2, 7, v9
	s_movk_i32 s0, 0xe0
	v_and_b32_e32 v4, 32, v128
	v_and_or_b32 v3, v2, s0, v0
	v_bitop3_b32 v10, v1, v4, 48 bitop3:0x6c
	v_and_b32_e32 v11, 64, v128
	v_bfe_u32 v13, v128, 2, 4
	s_movk_i32 s0, 0xf0
	s_lshr_b32 s6, s5, 6
	v_or_b32_e32 v1, v10, v11
	v_and_or_b32 v2, v2, s0, v13
	s_lshr_b32 s10, s5, 8
	s_lshl_b32 s44, s6, 10
	v_lshl_or_b32 v132, v2, 11, v1
	v_lshrrev_b32_e32 v2, 3, v128
	s_movk_i32 s0, 0x60
	s_add_u32 s45, s70, 0x3a00000
	v_and_or_b32 v0, v2, s0, v0
	s_movk_i32 s0, 0x70
	s_addc_u32 s46, s71, 0
	v_lshl_or_b32 v134, v0, 11, v1
	v_and_or_b32 v0, v2, s0, v13
	s_lshr_b32 s0, s3, 29
	s_add_i32 s0, s2, s0
	s_ashr_i32 s1, s0, 3
	s_and_b32 s0, s0, -8
	s_sub_i32 s0, s2, s0
	s_cmp_lt_i32 s0, 0
	s_movk_i32 s47, 0x161
	s_cselect_b32 s4, s47, 0x160
	s_mul_i32 s0, s0, s4
	s_add_i32 s0, s0, s1
	s_mul_hi_i32 s1, s0, 0x2e8ba2e9
	s_lshr_b32 s4, s1, 31
	s_ashr_i32 s1, s1, 5
	s_add_i32 s1, s1, s4
	s_lshl_b32 s7, s1, 3
	s_mulk_i32 s1, 0xb0
	s_sub_i32 s0, s0, s1
	s_bfe_u32 s1, s0, 0x3001c
	s_add_i32 s1, s0, s1
	s_sext_i32_i16 s4, s1
	s_and_b32 s1, s1, 0xfff8
	s_sub_i32 s0, s0, s1
	s_sext_i32_i16 s0, s0
	s_lshr_b32 s4, s4, 3
	s_add_i32 s30, s7, s0
	s_ashr_i32 s31, s30, 31
	s_bfe_i64 s[8:9], s[4:5], 0x100000
	s_lshl_b64 s[0:1], s[30:31], 19
	s_lshl_b64 s[8:9], s[8:9], 19
	s_add_u32 s38, s45, s8
	s_addc_u32 s39, s46, s9
	s_add_i32 s31, s44, 0
	s_add_i32 m0, s31, 0x10000
	v_lshl_or_b32 v130, v3, 11, v1
	global_load_lds_dwordx4 v134, s[38:39]
	s_add_i32 m0, s31, 0x12000
	s_add_u32 s8, s38, 0x40000
	global_load_lds_dwordx4 v130, s[38:39]
	s_addc_u32 s9, s39, 0
	s_add_i32 m0, s31, 0x14000
	v_lshl_or_b32 v136, v0, 11, v1
	global_load_lds_dwordx4 v134, s[8:9]
	s_add_i32 m0, s31, 0x16000
	s_add_u32 s36, s14, s0
	s_addc_u32 s37, s15, s1
	s_add_i32 s48, s31, 0x2000
	global_load_lds_dwordx4 v130, s[8:9]
	s_mov_b32 m0, s31
	s_add_u32 s0, s36, 0x40000
	global_load_lds_dwordx4 v136, s[36:37]
	s_mov_b32 m0, s48
	s_addc_u32 s1, s37, 0
	s_add_i32 s49, s31, 0x4000
	global_load_lds_dwordx4 v132, s[36:37]
	s_mov_b32 m0, s49
	s_add_i32 s50, s31, 0x6000
	global_load_lds_dwordx4 v136, s[0:1]
	s_mov_b32 m0, s50
	v_mov_b32_e32 v135, 0
	global_load_lds_dwordx4 v132, s[0:1]
	v_mov_b32_e32 v131, v135
	v_mov_b32_e32 v137, v135
	v_mov_b32_e32 v133, v135
	s_cmp_eq_u32 s10, 1
	s_mov_b32 s12, 0
	v_lshl_add_u64 v[6:7], s[38:39], 0, v[134:135]
	v_lshl_add_u64 v[4:5], s[38:39], 0, v[130:131]
	v_lshl_add_u64 v[0:1], s[36:37], 0, v[136:137]
	s_cselect_b64 s[0:1], -1, 0
	v_lshl_add_u64 v[2:3], s[36:37], 0, v[132:133]
	s_lshl_b32 s6, s6, 5
	s_and_b32 s22, s6, 0x60
	s_mov_b64 s[6:7], 0x80
	s_add_i32 m0, s31, 0x18000
	v_lshl_add_u64 v[6:7], v[6:7], 0, s[6:7]
	s_lshl_b32 s11, s10, 13
	s_lshl_b32 s23, s22, 7
	global_load_lds_dwordx4 v[6:7], off
	v_lshl_add_u64 v[4:5], v[4:5], 0, s[6:7]
	s_add_i32 m0, s31, 0x1a000
	s_add_i32 s51, s31, 0x8000
	s_add_i32 s52, s31, 0xa000
	global_load_lds_dwordx4 v[4:5], off
	v_lshl_add_u64 v[0:1], v[0:1], 0, s[6:7]
	s_mov_b32 m0, s51
	s_add_u32 s8, s38, 0x40080
	global_load_lds_dwordx4 v[0:1], off
	v_lshl_add_u64 v[0:1], v[2:3], 0, s[6:7]
	s_mov_b32 m0, s52
	s_addc_u32 s9, s39, 0
	global_load_lds_dwordx4 v[0:1], off
	s_add_i32 m0, s31, 0x1c000
	v_lshl_add_u64 v[0:1], s[8:9], 0, v[134:135]
	global_load_lds_dwordx4 v[0:1], off
	v_lshl_add_u64 v[0:1], s[8:9], 0, v[130:131]
	s_add_i32 m0, s31, 0x1e000
	s_sext_i32_i16 s13, s4
	global_load_lds_dwordx4 v[0:1], off
	v_lshlrev_b32_e32 v116, 2, v128
	v_add_u32_e32 v116, 0x20000, v116
	s_waitcnt vmcnt(34)
	v_pk_add_f32 v[118:119], v[18:19], v[22:23]
	v_pk_add_f32 v[120:121], v[16:17], v[20:21]
	v_pk_add_f32 v[122:123], v[26:27], v[30:31]
	v_pk_add_f32 v[124:125], v[24:25], v[28:29]
	v_pk_add_f32 v[118:119], v[118:119], v[122:123]
	v_pk_add_f32 v[120:121], v[120:121], v[124:125]
	v_add_f32_e32 v120, v121, v120
	v_add_f32_e32 v118, v118, v119
	v_add_f32_e32 v118, v120, v118
	v_fmamk_f32 v118, v118, 0x3a800000, v115
	v_rsq_f32_e32 v118, v118
	ds_write_b32 v116, v118
	s_waitcnt vmcnt(30)
	v_pk_add_f32 v[118:119], v[34:35], v[38:39]
	v_pk_add_f32 v[120:121], v[32:33], v[36:37]
	v_pk_add_f32 v[122:123], v[42:43], v[46:47]
	v_pk_add_f32 v[124:125], v[40:41], v[44:45]
	v_pk_add_f32 v[118:119], v[118:119], v[122:123]
	v_pk_add_f32 v[120:121], v[120:121], v[124:125]
	v_add_f32_e32 v120, v121, v120
	v_add_f32_e32 v118, v118, v119
	v_add_f32_e32 v118, v120, v118
	v_fmamk_f32 v118, v118, 0x3a800000, v115
	v_rsq_f32_e32 v118, v118
	ds_write_b32 v116, v118 offset:2048
	s_waitcnt vmcnt(26)
	v_pk_add_f32 v[118:119], v[50:51], v[54:55]
	v_pk_add_f32 v[120:121], v[48:49], v[52:53]
	v_pk_add_f32 v[122:123], v[58:59], v[62:63]
	v_pk_add_f32 v[124:125], v[56:57], v[60:61]
	v_pk_add_f32 v[118:119], v[118:119], v[122:123]
	v_pk_add_f32 v[120:121], v[120:121], v[124:125]
	v_add_f32_e32 v120, v121, v120
	v_add_f32_e32 v118, v118, v119
	v_add_f32_e32 v118, v120, v118
	v_fmamk_f32 v118, v118, 0x3a800000, v115
	v_rsq_f32_e32 v118, v118
	ds_write_b32 v116, v118 offset:4096
	s_waitcnt vmcnt(22)
	v_pk_add_f32 v[118:119], v[66:67], v[70:71]
	v_pk_add_f32 v[120:121], v[64:65], v[68:69]
	v_pk_add_f32 v[122:123], v[74:75], v[78:79]
	v_pk_add_f32 v[124:125], v[72:73], v[76:77]
	v_pk_add_f32 v[118:119], v[118:119], v[122:123]
	v_pk_add_f32 v[120:121], v[120:121], v[124:125]
	v_add_f32_e32 v120, v121, v120
	v_add_f32_e32 v118, v118, v119
	v_add_f32_e32 v118, v120, v118
	v_fmamk_f32 v118, v118, 0x3a800000, v115
	v_rsq_f32_e32 v118, v118
	ds_write_b32 v116, v118 offset:6144
	s_waitcnt vmcnt(18)
	v_pk_add_f32 v[118:119], v[82:83], v[86:87]
	v_pk_add_f32 v[120:121], v[80:81], v[84:85]
	v_pk_add_f32 v[122:123], v[90:91], v[94:95]
	v_pk_add_f32 v[124:125], v[88:89], v[92:93]
	v_pk_add_f32 v[118:119], v[118:119], v[122:123]
	v_pk_add_f32 v[120:121], v[120:121], v[124:125]
	v_add_f32_e32 v120, v121, v120
	v_add_f32_e32 v118, v118, v119
	v_add_f32_e32 v118, v120, v118
	v_fmamk_f32 v118, v118, 0x3a800000, v115
	v_rsq_f32_e32 v118, v118
	ds_write_b32 v116, v118 offset:8192
	s_waitcnt vmcnt(14)
	v_pk_add_f32 v[118:119], v[98:99], v[102:103]
	v_pk_add_f32 v[120:121], v[96:97], v[100:101]
	v_pk_add_f32 v[122:123], v[106:107], v[110:111]
	v_pk_add_f32 v[124:125], v[104:105], v[108:109]
	v_pk_add_f32 v[118:119], v[118:119], v[122:123]
	v_pk_add_f32 v[120:121], v[120:121], v[124:125]
	v_add_f32_e32 v120, v121, v120
	v_add_f32_e32 v118, v118, v119
	v_add_f32_e32 v118, v120, v118
	v_fmamk_f32 v118, v118, 0x3a800000, v115
	v_rsq_f32_e32 v118, v118
	ds_write_b32 v116, v118 offset:10240
	s_cmp_lg_u32 s10, 1
	s_cbranch_scc1 .LBB0_1641
	s_barrier

.LBB0_1809:
	s_cmp_lt_i32 s74, 20
	s_cselect_b64 s[0:1], -1, 0
	s_cmp_gt_i32 s75, 19
	s_cselect_b64 s[4:5], -1, 0
	s_and_b64 s[0:1], s[0:1], s[4:5]
	s_andn2_b64 vcc, exec, s[0:1]
	s_cbranch_vccnz .LBB0_1918
	s_waitcnt vmcnt(0)
	v_lshlrev_b32_e32 v8, 2, v128
	s_ashr_i32 s3, s2, 31
	v_add_u32_e32 v0, 0, v8
	s_ashr_i32 s48, s72, 31
	s_mov_b32 s49, s72
	v_and_b32_e32 v4, 0xff, v128
	v_add_u32_e32 v5, 0xfffffe00, v128
	v_add_u32_e32 v6, 0x20000, v0
	v_lshrrev_b32_e32 v7, 8, v128
	s_mov_b64 s[0:1], 0
	s_waitcnt lgkmcnt(0)
	v_mov_b64_e32 v[0:1], s[2:3]
	s_mov_b64 s[4:5], 0x600
	s_mov_b32 s10, 0x2aaaaaab
	s_movk_i32 s11, 0x60
	v_mov_b32_e32 v9, 0x358637bd
	s_movk_i32 s12, 0x8ff
	v_mov_b32_e32 v10, 0xc0
	v_mov_b32_e32 v11, 0xc1
	v_and_b32_e32 v114, 0xff, v128
	s_lshr_b32 s98, s91, 2
	v_mov_b32_e32 v115, 0x358637bd
	s_mul_i32 s99, s98, s72
	s_add_i32 s99, s99, s2
	s_cmp_lt_u32 s99, 0x600
	s_cselect_b32 s99, s99, s2
	s_and_b32 s100, s99, 7
	s_mul_i32 s100, s100, 0xc0
	s_lshr_b32 s101, s99, 3
	s_add_i32 s100, s100, s101
	s_mul_hi_u32 s101, s100, 0x2aaaaab
	s_lshl_b32 s101, s101, 3
	s_and_b32 s100, s100, 7
	s_or_b32 s101, s101, s100
	s_lshl_b32 s101, s101, 8
	v_add_u32_e32 v112, s101, v114
	v_lshlrev_b32_e32 v112, 6, v112
	v_mov_b32_e32 v113, 0
	v_lshl_add_u64 v[112:113], s[18:19], 0, v[112:113]
	global_load_dwordx4 v[16:19], v[112:113], off
	global_load_dwordx4 v[20:23], v[112:113], off offset:16
	global_load_dwordx4 v[24:27], v[112:113], off offset:32
	global_load_dwordx4 v[28:31], v[112:113], off offset:48
	s_add_i32 s98, s98, 2
	s_mul_i32 s99, s98, s72
	s_add_i32 s99, s99, s2
	s_cmp_lt_u32 s99, 0x600
	s_cselect_b32 s99, s99, s2
	s_and_b32 s100, s99, 7
	s_mul_i32 s100, s100, 0xc0
	s_lshr_b32 s101, s99, 3
	s_add_i32 s100, s100, s101
	s_mul_hi_u32 s101, s100, 0x2aaaaab
	s_lshl_b32 s101, s101, 3
	s_and_b32 s100, s100, 7
	s_or_b32 s101, s101, s100
	s_lshl_b32 s101, s101, 8
	v_add_u32_e32 v112, s101, v114
	v_lshlrev_b32_e32 v112, 6, v112
	v_mov_b32_e32 v113, 0
	v_lshl_add_u64 v[112:113], s[18:19], 0, v[112:113]
	global_load_dwordx4 v[32:35], v[112:113], off
	global_load_dwordx4 v[36:39], v[112:113], off offset:16
	global_load_dwordx4 v[40:43], v[112:113], off offset:32
	global_load_dwordx4 v[44:47], v[112:113], off offset:48
	s_add_i32 s98, s98, 2
	s_mul_i32 s99, s98, s72
	s_add_i32 s99, s99, s2
	s_cmp_lt_u32 s99, 0x600
	s_cselect_b32 s99, s99, s2
	s_and_b32 s100, s99, 7
	s_mul_i32 s100, s100, 0xc0
	s_lshr_b32 s101, s99, 3
	s_add_i32 s100, s100, s101
	s_mul_hi_u32 s101, s100, 0x2aaaaab
	s_lshl_b32 s101, s101, 3
	s_and_b32 s100, s100, 7
	s_or_b32 s101, s101, s100
	s_lshl_b32 s101, s101, 8
	v_add_u32_e32 v112, s101, v114
	v_lshlrev_b32_e32 v112, 6, v112
	v_mov_b32_e32 v113, 0
	v_lshl_add_u64 v[112:113], s[18:19], 0, v[112:113]
	global_load_dwordx4 v[48:51], v[112:113], off
	global_load_dwordx4 v[52:55], v[112:113], off offset:16
	global_load_dwordx4 v[56:59], v[112:113], off offset:32
	global_load_dwordx4 v[60:63], v[112:113], off offset:48
	s_add_i32 s98, s98, 2

.LBB0_1818:
	v_lshrrev_b32_e32 v2, 1, v128
	v_and_b32_e32 v130, 24, v2
	v_lshrrev_b32_e32 v2, 5, v128
	v_and_b32_e32 v2, 4, v2
	v_bfe_u32 v3, v128, 2, 2
	v_lshlrev_b32_e32 v0, 4, v128
	v_and_b32_e32 v1, 32, v128
	v_bfe_u32 v11, v128, 2, 4
	v_or3_b32 v2, v2, v3, v130
	v_lshrrev_b32_e32 v3, 3, v128
	s_movk_i32 s1, 0x70
	v_bitop3_b32 v9, v0, v1, 48 bitop3:0x6c
	v_and_b32_e32 v10, 64, v128
	v_and_or_b32 v4, v3, s1, v11
	s_movk_i32 s1, 0x60
	v_add_u32_e32 v12, 0x2000, v0
	s_lshr_b32 s5, s8, 6
	s_lshr_b32 s4, s8, 8
	v_or_b32_e32 v1, v9, v10
	v_and_or_b32 v3, v3, s1, v2
	v_lshrrev_b32_e32 v0, 7, v12
	s_movk_i32 s1, 0xf0
	s_lshl_b32 s50, s5, 10
	v_lshl_or_b32 v134, v3, 11, v1
	v_and_or_b32 v3, v0, s1, v11
	s_movk_i32 s1, 0xe0
	s_add_u32 s51, s70, 0x4a80000
	v_and_or_b32 v0, v0, s1, v2
	s_addc_u32 s52, s71, 0
	s_ashr_i32 s7, s6, 31
	s_ashr_i32 s1, s0, 31
	s_lshl_b64 s[10:11], s[6:7], 19
	s_lshl_b64 s[12:13], s[0:1], 19
	s_add_u32 s44, s51, s12
	s_addc_u32 s45, s52, s13
	s_add_i32 s53, s50, 0
	s_add_i32 m0, s53, 0x10000
	v_lshl_or_b32 v138, v0, 11, v1
	global_load_lds_dwordx4 v134, s[44:45]
	s_add_i32 m0, s53, 0x12000
	s_add_u32 s12, s44, 0x40000
	global_load_lds_dwordx4 v138, s[44:45]
	s_addc_u32 s13, s45, 0
	s_add_i32 m0, s53, 0x14000
	v_lshl_or_b32 v132, v4, 11, v1
	global_load_lds_dwordx4 v134, s[12:13]
	s_add_i32 m0, s53, 0x16000
	s_add_u32 s42, s14, s10
	s_addc_u32 s43, s15, s11
	s_add_i32 s54, s53, 0x2000
	global_load_lds_dwordx4 v138, s[12:13]
	s_mov_b32 m0, s53
	s_add_u32 s10, s42, 0x40000
	v_lshl_or_b32 v136, v3, 11, v1
	global_load_lds_dwordx4 v132, s[42:43]
	s_mov_b32 m0, s54
	s_addc_u32 s11, s43, 0
	s_add_i32 s55, s53, 0x4000
	global_load_lds_dwordx4 v136, s[42:43]
	s_mov_b32 m0, s55
	s_add_i32 s56, s53, 0x6000
	global_load_lds_dwordx4 v132, s[10:11]
	s_mov_b32 m0, s56
	v_mov_b32_e32 v141, 0
	global_load_lds_dwordx4 v136, s[10:11]
	v_mov_b32_e32 v135, v141
	v_mov_b32_e32 v139, v141
	v_mov_b32_e32 v133, v141
	v_mov_b32_e32 v137, v141
	s_cmp_eq_u32 s4, 1
	s_mov_b32 s9, 0
	v_lshl_add_u64 v[6:7], s[44:45], 0, v[134:135]
	v_lshl_add_u64 v[4:5], s[44:45], 0, v[138:139]
	v_lshl_add_u64 v[0:1], s[42:43], 0, v[132:133]
	s_cselect_b64 s[10:11], -1, 0
	v_lshl_add_u64 v[2:3], s[42:43], 0, v[136:137]
	s_add_u32 s22, s70, 0x13700000
	s_addc_u32 s23, s71, 0
	s_lshl_b32 s5, s5, 5
	s_mov_b64 s[26:27], 0x80
	s_and_b32 s57, s5, 0x60
	s_add_i32 m0, s53, 0x18000
	v_lshl_add_u64 v[6:7], v[6:7], 0, s[26:27]
	s_lshl_b32 s1, s4, 13
	s_lshl_b32 s5, s57, 7
	global_load_lds_dwordx4 v[6:7], off
	v_lshl_add_u64 v[4:5], v[4:5], 0, s[26:27]
	s_add_i32 m0, s53, 0x1a000
	s_add_i32 s58, s53, 0x8000
	s_add_i32 s59, s53, 0xa000
	global_load_lds_dwordx4 v[4:5], off
	v_lshl_add_u64 v[0:1], v[0:1], 0, s[26:27]
	s_mov_b32 m0, s58
	s_add_u32 s12, s44, 0x40080
	global_load_lds_dwordx4 v[0:1], off
	v_lshl_add_u64 v[0:1], v[2:3], 0, s[26:27]
	s_mov_b32 m0, s59
	s_addc_u32 s13, s45, 0
	global_load_lds_dwordx4 v[0:1], off
	s_add_i32 m0, s53, 0x1c000
	v_lshl_add_u64 v[0:1], s[12:13], 0, v[134:135]
	global_load_lds_dwordx4 v[0:1], off
	v_lshl_add_u64 v[0:1], s[12:13], 0, v[138:139]
	s_add_i32 m0, s53, 0x1e000
	global_load_lds_dwordx4 v[0:1], off
	v_lshlrev_b32_e32 v116, 2, v128
	v_add_u32_e32 v116, 0x20000, v116
	s_waitcnt vmcnt(22)
	v_pk_add_f32 v[118:119], v[18:19], v[22:23]
	v_pk_add_f32 v[120:121], v[16:17], v[20:21]
	v_pk_add_f32 v[122:123], v[26:27], v[30:31]
	v_pk_add_f32 v[124:125], v[24:25], v[28:29]
	v_pk_add_f32 v[118:119], v[118:119], v[122:123]
	v_pk_add_f32 v[120:121], v[120:121], v[124:125]
	v_add_f32_e32 v120, v121, v120
	v_add_f32_e32 v118, v118, v119
	v_add_f32_e32 v118, v120, v118
	v_fmamk_f32 v118, v118, 0x3a800000, v115
	v_rsq_f32_e32 v118, v118
	ds_write_b32 v116, v118
	s_waitcnt vmcnt(18)
	v_pk_add_f32 v[118:119], v[34:35], v[38:39]
	v_pk_add_f32 v[120:121], v[32:33], v[36:37]
	v_pk_add_f32 v[122:123], v[42:43], v[46:47]
	v_pk_add_f32 v[124:125], v[40:41], v[44:45]
	v_pk_add_f32 v[118:119], v[118:119], v[122:123]
	v_pk_add_f32 v[120:121], v[120:121], v[124:125]
	v_add_f32_e32 v120, v121, v120
	v_add_f32_e32 v118, v118, v119
	v_add_f32_e32 v118, v120, v118
	v_fmamk_f32 v118, v118, 0x3a800000, v115
	v_rsq_f32_e32 v118, v118
	ds_write_b32 v116, v118 offset:2048
	s_waitcnt vmcnt(14)
	v_pk_add_f32 v[118:119], v[50:51], v[54:55]
	v_pk_add_f32 v[120:121], v[48:49], v[52:53]
	v_pk_add_f32 v[122:123], v[58:59], v[62:63]
	v_pk_add_f32 v[124:125], v[56:57], v[60:61]
	v_pk_add_f32 v[118:119], v[118:119], v[122:123]
	v_pk_add_f32 v[120:121], v[120:121], v[124:125]
	v_add_f32_e32 v120, v121, v120
	v_add_f32_e32 v118, v118, v119
	v_add_f32_e32 v118, v120, v118
	v_fmamk_f32 v118, v118, 0x3a800000, v115
	v_rsq_f32_e32 v118, v118
	ds_write_b32 v116, v118 offset:4096
	s_cmp_lg_u32 s4, 1
	s_cbranch_scc1 .LBB0_1820
	s_barrier

.LBB0_2077:
	s_cmp_lt_i32 s74, 23
	s_cselect_b64 s[0:1], -1, 0
	s_cmp_gt_i32 s75, 22
	s_cselect_b64 s[4:5], -1, 0
	s_and_b64 s[0:1], s[0:1], s[4:5]
	s_andn2_b64 vcc, exec, s[0:1]
	s_cbranch_vccnz .LBB0_2152
	s_waitcnt vmcnt(0)
	v_lshlrev_b32_e32 v8, 2, v128
	s_ashr_i32 s3, s2, 31
	v_add_u32_e32 v0, 0, v8
	s_ashr_i32 s36, s72, 31
	s_mov_b32 s37, s72
	v_and_b32_e32 v4, 0xff, v128
	v_add_u32_e32 v5, 0xfffffe00, v128
	v_add_u32_e32 v6, 0x20000, v0
	s_mov_b64 s[0:1], 0
	s_waitcnt lgkmcnt(0)
	v_mov_b64_e32 v[0:1], s[2:3]
	s_mov_b64 s[4:5], 0xb00
	s_mov_b32 s10, 0x2e8ba2e9
	s_movk_i32 s11, 0xb0
	v_mov_b32_e32 v7, 0x358637bd
	s_movk_i32 s12, 0x8ff
	v_mov_b32_e32 v9, 0x160
	v_mov_b32_e32 v10, 0x161
	v_and_b32_e32 v114, 0xff, v128
	s_lshr_b32 s98, s91, 2
	v_mov_b32_e32 v115, 0x358637bd
	s_mul_i32 s99, s98, s72
	s_add_i32 s99, s99, s2
	s_cmp_lt_u32 s99, 0xb00
	s_cselect_b32 s99, s99, s2
	s_and_b32 s100, s99, 7
	s_mul_i32 s100, s100, 0x160
	s_lshr_b32 s101, s99, 3
	s_add_i32 s100, s100, s101
	s_mul_hi_u32 s101, s100, 0x1745d18
	s_lshl_b32 s101, s101, 3
	s_and_b32 s100, s100, 7
	s_or_b32 s101, s101, s100
	s_lshl_b32 s101, s101, 8
	v_add_u32_e32 v112, s101, v114
	v_lshlrev_b32_e32 v112, 6, v112
	v_mov_b32_e32 v113, 0
	v_lshl_add_u64 v[112:113], s[18:19], 0, v[112:113]
	global_load_dwordx4 v[16:19], v[112:113], off
	global_load_dwordx4 v[20:23], v[112:113], off offset:16
	global_load_dwordx4 v[24:27], v[112:113], off offset:32
	global_load_dwordx4 v[28:31], v[112:113], off offset:48
	s_add_i32 s98, s98, 2
	s_mul_i32 s99, s98, s72
	s_add_i32 s99, s99, s2
	s_cmp_lt_u32 s99, 0xb00
	s_cselect_b32 s99, s99, s2
	s_and_b32 s100, s99, 7
	s_mul_i32 s100, s100, 0x160
	s_lshr_b32 s101, s99, 3
	s_add_i32 s100, s100, s101
	s_mul_hi_u32 s101, s100, 0x1745d18
	s_lshl_b32 s101, s101, 3
	s_and_b32 s100, s100, 7
	s_or_b32 s101, s101, s100
	s_lshl_b32 s101, s101, 8
	v_add_u32_e32 v112, s101, v114
	v_lshlrev_b32_e32 v112, 6, v112
	v_mov_b32_e32 v113, 0
	v_lshl_add_u64 v[112:113], s[18:19], 0, v[112:113]
	global_load_dwordx4 v[32:35], v[112:113], off
	global_load_dwordx4 v[36:39], v[112:113], off offset:16
	global_load_dwordx4 v[40:43], v[112:113], off offset:32
	global_load_dwordx4 v[44:47], v[112:113], off offset:48
	s_add_i32 s98, s98, 2
	s_mul_i32 s99, s98, s72
	s_add_i32 s99, s99, s2
	s_cmp_lt_u32 s99, 0xb00
	s_cselect_b32 s99, s99, s2
	s_and_b32 s100, s99, 7
	s_mul_i32 s100, s100, 0x160
	s_lshr_b32 s101, s99, 3
	s_add_i32 s100, s100, s101
	s_mul_hi_u32 s101, s100, 0x1745d18
	s_lshl_b32 s101, s101, 3
	s_and_b32 s100, s100, 7
	s_or_b32 s101, s101, s100
	s_lshl_b32 s101, s101, 8
	v_add_u32_e32 v112, s101, v114
	v_lshlrev_b32_e32 v112, 6, v112
	v_mov_b32_e32 v113, 0
	v_lshl_add_u64 v[112:113], s[18:19], 0, v[112:113]
	global_load_dwordx4 v[48:51], v[112:113], off
	global_load_dwordx4 v[52:55], v[112:113], off offset:16
	global_load_dwordx4 v[56:59], v[112:113], off offset:32
	global_load_dwordx4 v[60:63], v[112:113], off offset:48
	s_add_i32 s98, s98, 2
	s_mul_i32 s99, s98, s72
	s_add_i32 s99, s99, s2
	s_cmp_lt_u32 s99, 0xb00
	s_cselect_b32 s99, s99, s2
	s_and_b32 s100, s99, 7
	s_mul_i32 s100, s100, 0x160
	s_lshr_b32 s101, s99, 3
	s_add_i32 s100, s100, s101
	s_mul_hi_u32 s101, s100, 0x1745d18
	s_lshl_b32 s101, s101, 3
	s_and_b32 s100, s100, 7
	s_or_b32 s101, s101, s100
	s_lshl_b32 s101, s101, 8
	v_add_u32_e32 v112, s101, v114
	v_lshlrev_b32_e32 v112, 6, v112
	v_mov_b32_e32 v113, 0
	v_lshl_add_u64 v[112:113], s[18:19], 0, v[112:113]
	global_load_dwordx4 v[64:67], v[112:113], off
	global_load_dwordx4 v[68:71], v[112:113], off offset:16
	global_load_dwordx4 v[72:75], v[112:113], off offset:32
	global_load_dwordx4 v[76:79], v[112:113], off offset:48
	s_add_i32 s98, s98, 2
	s_mul_i32 s99, s98, s72
	s_add_i32 s99, s99, s2
	s_cmp_lt_u32 s99, 0xb00
	s_cselect_b32 s99, s99, s2
	s_and_b32 s100, s99, 7
	s_mul_i32 s100, s100, 0x160
	s_lshr_b32 s101, s99, 3
	s_add_i32 s100, s100, s101
	s_mul_hi_u32 s101, s100, 0x1745d18
	s_lshl_b32 s101, s101, 3
	s_and_b32 s100, s100, 7
	s_or_b32 s101, s101, s100
	s_lshl_b32 s101, s101, 8
	v_add_u32_e32 v112, s101, v114
	v_lshlrev_b32_e32 v112, 6, v112
	v_mov_b32_e32 v113, 0
	v_lshl_add_u64 v[112:113], s[18:19], 0, v[112:113]
	global_load_dwordx4 v[80:83], v[112:113], off
	global_load_dwordx4 v[84:87], v[112:113], off offset:16
	global_load_dwordx4 v[88:91], v[112:113], off offset:32
	global_load_dwordx4 v[92:95], v[112:113], off offset:48
	s_add_i32 s98, s98, 2
	s_mul_i32 s99, s98, s72
	s_add_i32 s99, s99, s2
	s_cmp_lt_u32 s99, 0xb00
	s_cselect_b32 s99, s99, s2
	s_and_b32 s100, s99, 7
	s_mul_i32 s100, s100, 0x160
	s_lshr_b32 s101, s99, 3
	s_add_i32 s100, s100, s101
	s_mul_hi_u32 s101, s100, 0x1745d18
	s_lshl_b32 s101, s101, 3
	s_and_b32 s100, s100, 7
	s_or_b32 s101, s101, s100
	s_lshl_b32 s101, s101, 8
	v_add_u32_e32 v112, s101, v114
	v_lshlrev_b32_e32 v112, 6, v112
	v_mov_b32_e32 v113, 0
	v_lshl_add_u64 v[112:113], s[18:19], 0, v[112:113]
	global_load_dwordx4 v[96:99], v[112:113], off
	global_load_dwordx4 v[100:103], v[112:113], off offset:16
	global_load_dwordx4 v[104:107], v[112:113], off offset:32
	global_load_dwordx4 v[108:111], v[112:113], off offset:48
	s_add_i32 s98, s98, 2
.LBB0_2082:
	s_or_b64 exec, exec, s[0:1]
	s_cmpk_gt_i32 s2, 0xaff
	v_readfirstlane_b32 s5, v128
	s_barrier
	s_cbranch_scc1 .LBB0_2098
	v_lshrrev_b32_e32 v0, 5, v128
	v_lshrrev_b32_e32 v2, 1, v128
	v_and_b32_e32 v0, 4, v0
	v_bfe_u32 v1, v128, 2, 2
	v_and_b32_e32 v12, 24, v2
	v_or3_b32 v0, v0, v1, v12
	v_lshlrev_b32_e32 v1, 4, v128
	v_add_u32_e32 v9, 0x2000, v1
	v_lshrrev_b32_e32 v2, 7, v9
	s_movk_i32 s0, 0xe0
	v_and_b32_e32 v4, 32, v128
	v_and_or_b32 v3, v2, s0, v0
	v_bitop3_b32 v10, v1, v4, 48 bitop3:0x6c
	v_and_b32_e32 v11, 64, v128
	v_bfe_u32 v13, v128, 2, 4
	s_movk_i32 s0, 0xf0
	s_lshr_b32 s6, s5, 6
	v_or_b32_e32 v1, v10, v11
	v_and_or_b32 v2, v2, s0, v13
	s_lshr_b32 s10, s5, 8
	s_lshl_b32 s38, s6, 10
	v_lshl_or_b32 v132, v2, 11, v1
	v_lshrrev_b32_e32 v2, 3, v128
	s_movk_i32 s0, 0x60
	s_add_u32 s39, s70, 0x5280000
	v_and_or_b32 v0, v2, s0, v0
	s_movk_i32 s0, 0x70
	s_addc_u32 s40, s71, 0
	v_lshl_or_b32 v134, v0, 11, v1
	v_and_or_b32 v0, v2, s0, v13
	s_lshr_b32 s0, s3, 29
	s_add_i32 s0, s2, s0
	s_ashr_i32 s1, s0, 3
	s_and_b32 s0, s0, -8
	s_sub_i32 s0, s2, s0
	s_cmp_lt_i32 s0, 0
	s_movk_i32 s41, 0x161
	s_cselect_b32 s4, s41, 0x160
	s_mul_i32 s0, s0, s4
	s_add_i32 s0, s0, s1
	s_mul_hi_i32 s1, s0, 0x2e8ba2e9
	s_lshr_b32 s4, s1, 31
	s_ashr_i32 s1, s1, 5
	s_add_i32 s1, s1, s4
	s_lshl_b32 s7, s1, 3
	s_mulk_i32 s1, 0xb0
	s_sub_i32 s0, s0, s1
	s_bfe_u32 s1, s0, 0x3001c
	s_add_i32 s1, s0, s1
	s_sext_i32_i16 s4, s1
	s_and_b32 s1, s1, 0xfff8
	s_sub_i32 s0, s0, s1
	s_sext_i32_i16 s0, s0
	s_lshr_b32 s4, s4, 3
	s_add_i32 s24, s7, s0
	s_ashr_i32 s25, s24, 31
	s_bfe_i64 s[8:9], s[4:5], 0x100000
	s_lshl_b64 s[0:1], s[24:25], 19
	s_lshl_b64 s[8:9], s[8:9], 19
	s_add_u32 s28, s39, s8
	s_addc_u32 s29, s40, s9
	s_add_i32 s25, s38, 0
	s_add_i32 m0, s25, 0x10000
	v_lshl_or_b32 v130, v3, 11, v1
	global_load_lds_dwordx4 v134, s[28:29]
	s_add_i32 m0, s25, 0x12000
	s_add_u32 s8, s28, 0x40000
	global_load_lds_dwordx4 v130, s[28:29]
	s_addc_u32 s9, s29, 0
	s_add_i32 m0, s25, 0x14000
	v_lshl_or_b32 v136, v0, 11, v1
	global_load_lds_dwordx4 v134, s[8:9]
	s_add_i32 m0, s25, 0x16000
	s_add_u32 s26, s14, s0
	s_addc_u32 s27, s15, s1
	s_add_i32 s42, s25, 0x2000
	global_load_lds_dwordx4 v130, s[8:9]
	s_mov_b32 m0, s25
	s_add_u32 s0, s26, 0x40000
	global_load_lds_dwordx4 v136, s[26:27]
	s_mov_b32 m0, s42
	s_addc_u32 s1, s27, 0
	s_add_i32 s43, s25, 0x4000
	global_load_lds_dwordx4 v132, s[26:27]
	s_mov_b32 m0, s43
	s_add_i32 s44, s25, 0x6000
	global_load_lds_dwordx4 v136, s[0:1]
	s_mov_b32 m0, s44
	v_mov_b32_e32 v135, 0
	global_load_lds_dwordx4 v132, s[0:1]
	v_mov_b32_e32 v131, v135
	v_mov_b32_e32 v137, v135
	v_mov_b32_e32 v133, v135
	s_cmp_eq_u32 s10, 1
	s_mov_b32 s12, 0
	v_lshl_add_u64 v[6:7], s[28:29], 0, v[134:135]
	v_lshl_add_u64 v[4:5], s[28:29], 0, v[130:131]
	v_lshl_add_u64 v[0:1], s[26:27], 0, v[136:137]
	s_cselect_b64 s[0:1], -1, 0
	v_lshl_add_u64 v[2:3], s[26:27], 0, v[132:133]
	s_lshl_b32 s6, s6, 5
	s_and_b32 s18, s6, 0x60
	s_mov_b64 s[6:7], 0x80
	s_add_i32 m0, s25, 0x18000
	v_lshl_add_u64 v[6:7], v[6:7], 0, s[6:7]
	s_lshl_b32 s11, s10, 13
	s_lshl_b32 s19, s18, 7
	global_load_lds_dwordx4 v[6:7], off
	v_lshl_add_u64 v[4:5], v[4:5], 0, s[6:7]
	s_add_i32 m0, s25, 0x1a000
	s_add_i32 s45, s25, 0x8000
	s_add_i32 s46, s25, 0xa000
	global_load_lds_dwordx4 v[4:5], off
	v_lshl_add_u64 v[0:1], v[0:1], 0, s[6:7]
	s_mov_b32 m0, s45
	s_add_u32 s8, s28, 0x40080
	global_load_lds_dwordx4 v[0:1], off
	v_lshl_add_u64 v[0:1], v[2:3], 0, s[6:7]
	s_mov_b32 m0, s46
	s_addc_u32 s9, s29, 0
	global_load_lds_dwordx4 v[0:1], off
	s_add_i32 m0, s25, 0x1c000
	v_lshl_add_u64 v[0:1], s[8:9], 0, v[134:135]
	global_load_lds_dwordx4 v[0:1], off
	v_lshl_add_u64 v[0:1], s[8:9], 0, v[130:131]
	s_add_i32 m0, s25, 0x1e000
	s_sext_i32_i16 s13, s4
	global_load_lds_dwordx4 v[0:1], off
	v_lshlrev_b32_e32 v116, 2, v128
	v_add_u32_e32 v116, 0x20000, v116
	s_waitcnt vmcnt(34)
	v_pk_add_f32 v[118:119], v[18:19], v[22:23]
	v_pk_add_f32 v[120:121], v[16:17], v[20:21]
	v_pk_add_f32 v[122:123], v[26:27], v[30:31]
	v_pk_add_f32 v[124:125], v[24:25], v[28:29]
	v_pk_add_f32 v[118:119], v[118:119], v[122:123]
	v_pk_add_f32 v[120:121], v[120:121], v[124:125]
	v_add_f32_e32 v120, v121, v120
	v_add_f32_e32 v118, v118, v119
	v_add_f32_e32 v118, v120, v118
	v_fmamk_f32 v118, v118, 0x3a800000, v115
	v_rsq_f32_e32 v118, v118
	ds_write_b32 v116, v118
	s_waitcnt vmcnt(30)
	v_pk_add_f32 v[118:119], v[34:35], v[38:39]
	v_pk_add_f32 v[120:121], v[32:33], v[36:37]
	v_pk_add_f32 v[122:123], v[42:43], v[46:47]
	v_pk_add_f32 v[124:125], v[40:41], v[44:45]
	v_pk_add_f32 v[118:119], v[118:119], v[122:123]
	v_pk_add_f32 v[120:121], v[120:121], v[124:125]
	v_add_f32_e32 v120, v121, v120
	v_add_f32_e32 v118, v118, v119
	v_add_f32_e32 v118, v120, v118
	v_fmamk_f32 v118, v118, 0x3a800000, v115
	v_rsq_f32_e32 v118, v118
	ds_write_b32 v116, v118 offset:2048
	s_waitcnt vmcnt(26)
	v_pk_add_f32 v[118:119], v[50:51], v[54:55]
	v_pk_add_f32 v[120:121], v[48:49], v[52:53]
	v_pk_add_f32 v[122:123], v[58:59], v[62:63]
	v_pk_add_f32 v[124:125], v[56:57], v[60:61]
	v_pk_add_f32 v[118:119], v[118:119], v[122:123]
	v_pk_add_f32 v[120:121], v[120:121], v[124:125]
	v_add_f32_e32 v120, v121, v120
	v_add_f32_e32 v118, v118, v119
	v_add_f32_e32 v118, v120, v118
	v_fmamk_f32 v118, v118, 0x3a800000, v115
	v_rsq_f32_e32 v118, v118
	ds_write_b32 v116, v118 offset:4096
	s_waitcnt vmcnt(22)
	v_pk_add_f32 v[118:119], v[66:67], v[70:71]
	v_pk_add_f32 v[120:121], v[64:65], v[68:69]
	v_pk_add_f32 v[122:123], v[74:75], v[78:79]
	v_pk_add_f32 v[124:125], v[72:73], v[76:77]
	v_pk_add_f32 v[118:119], v[118:119], v[122:123]
	v_pk_add_f32 v[120:121], v[120:121], v[124:125]
	v_add_f32_e32 v120, v121, v120
	v_add_f32_e32 v118, v118, v119
	v_add_f32_e32 v118, v120, v118
	v_fmamk_f32 v118, v118, 0x3a800000, v115
	v_rsq_f32_e32 v118, v118
	ds_write_b32 v116, v118 offset:6144
	s_waitcnt vmcnt(18)
	v_pk_add_f32 v[118:119], v[82:83], v[86:87]
	v_pk_add_f32 v[120:121], v[80:81], v[84:85]
	v_pk_add_f32 v[122:123], v[90:91], v[94:95]
	v_pk_add_f32 v[124:125], v[88:89], v[92:93]
	v_pk_add_f32 v[118:119], v[118:119], v[122:123]
	v_pk_add_f32 v[120:121], v[120:121], v[124:125]
	v_add_f32_e32 v120, v121, v120
	v_add_f32_e32 v118, v118, v119
	v_add_f32_e32 v118, v120, v118
	v_fmamk_f32 v118, v118, 0x3a800000, v115
	v_rsq_f32_e32 v118, v118
	ds_write_b32 v116, v118 offset:8192
	s_waitcnt vmcnt(14)
	v_pk_add_f32 v[118:119], v[98:99], v[102:103]
	v_pk_add_f32 v[120:121], v[96:97], v[100:101]
	v_pk_add_f32 v[122:123], v[106:107], v[110:111]
	v_pk_add_f32 v[124:125], v[104:105], v[108:109]
	v_pk_add_f32 v[118:119], v[118:119], v[122:123]
	v_pk_add_f32 v[120:121], v[120:121], v[124:125]
	v_add_f32_e32 v120, v121, v120
	v_add_f32_e32 v118, v118, v119
	v_add_f32_e32 v118, v120, v118
	v_fmamk_f32 v118, v118, 0x3a800000, v115
	v_rsq_f32_e32 v118, v118
	ds_write_b32 v116, v118 offset:10240
	s_cmp_lg_u32 s10, 1
	s_cbranch_scc1 .LBB0_2085
	s_barrier
.LBB0_2085:
	s_waitcnt vmcnt(8) lgkmcnt(0)
	s_barrier
	v_and_b32_e32 v0, 15, v128
	v_lshlrev_b32_e32 v1, 1, v12
	v_lshl_or_b32 v129, s10, 6, v0
	v_lshl_or_b32 v2, v0, 6, v1
	v_lshlrev_b32_e32 v0, 2, v0
	v_and_b32_e32 v3, 32, v0
	v_bitop3_b32 v2, v2, s11, v3 bitop3:0xde
	v_lshlrev_b32_e32 v3, 6, v128
	s_movk_i32 s4, 0x3c0
	s_cmpk_lt_u32 s5, 0x100
	v_and_or_b32 v1, v3, s4, v1
	s_cselect_b64 s[8:9], -1, 0
	s_lshl_b32 s4, s10, 8
	s_add_i32 s4, s4, 0
	s_add_i32 s4, s4, 0x20000
	v_and_b32_e32 v3, 32, v8
	v_add_u32_e32 v151, s4, v0
	v_lshlrev_b32_e32 v0, 8, v128
	v_bitop3_b32 v150, s19, v1, v3 bitop3:0xf6
	v_and_b32_e32 v0, 0x38000, v0
	v_lshlrev_b32_e32 v1, 11, v13
	v_or3_b32 v0, v10, v0, v1
	v_add_u32_e32 v138, v0, v11
	v_lshlrev_b32_e32 v0, 4, v9
	s_waitcnt vmcnt(6)
	v_and_b32_e32 v0, 0x78000, v0
	v_or3_b32 v0, v10, v0, v1
	s_add_i32 s47, 0, 0x10000
	s_add_i32 s48, 0, 0x14000
	v_or_b32_e32 v152, s18, v12
	v_mov_b32_e32 v139, v135
	v_add_u32_e32 v140, v0, v11
	v_mov_b32_e32 v141, v135
	v_mov_b64_e32 v[142:143], 0xb00
	v_mov_b64_e32 v[144:145], 0xaff
	v_add_u32_e32 v153, s47, v150
	v_add_u32_e32 v154, s48, v150
	v_add_u32_e32 v155, 0, v2
	s_movk_i32 s49, 0x1600
	s_mov_b32 s50, 0
	s_barrier
	s_branch .LBB0_2088
